# residual epilogues (out-proj, down-proj): per-row sum-of-squares atomics deferred to the end of the epilogue; out-proj epilogue issues both column-half x loads together
# speedup vs baseline: 1.0214x; 1.0106x over previous
; __device__ __forceinline__ unsigned cvt_pk_bf16(float lo, float hi) { unsigned r; asm volatile("v_cvt_pk_bf16_f32 %0, %1, %2" : "=v"(r) : "v"(lo), "v"(hi)); return r; }
;     __device__ __forceinline__ void final(const f32x4 (&acc)[2][2][4][2], const Unit& u, int ui, int wr, int wc, int fr, int fq) const {
;         const int row0 = u.pm * BM + wr * 64 + fr, col0 = u.pn * BM + wc * 32 + 8 * fq;
; #pragma unroll
;         for (int ai = 0; ai < 2; ++ai)
; #pragma unroll
;             for (int m = 0; m < 4; ++m) { const int row = row0 + ai * HALF + m * 16; const float f = tab[(ui * 256 + ai * HALF + wr * 64 + m * 16 + fr) * 4 + 2];
;                 const float* src = (row < 16384 ? srcA + (size_t)row * 2048 : srcB + (size_t)(row - 16384) * 2048) + col0; float s = 0.f;
; #pragma unroll
;                 for (int bj = 0; bj < 2; ++bj) { const f32x4 v0 = acc[ai][bj][m][0] * f + __builtin_nontemporal_load((const f32x4*)(src + bj * HALF)), v1 = acc[ai][bj][m][1] * f + __builtin_nontemporal_load((const f32x4*)(src + bj * HALF + 4));
;                     s += (v0[0] * v0[0] + v0[1] * v0[1]) + (v0[2] * v0[2] + v0[3] * v0[3]) + (v1[0] * v1[0] + v1[1] * v1[1]) + (v1[2] * v1[2] + v1[3] * v1[3]);
;                     u32x4 w; w.x = cvt_pk_bf16(v0[0], v0[1]); w.y = cvt_pk_bf16(v0[2], v0[3]); w.z = cvt_pk_bf16(v1[0], v1[1]); w.w = cvt_pk_bf16(v1[2], v1[3]);
;                     *(u32x4*)(xb + (size_t)row * 2048 + col0 + bj * HALF) = w; }
;                 s = sum_x32(sum_x16(s)); asm volatile("" : "+v"(s));
;                 if (fq == 0) atomicAdd(ss + row, s); }
;     }
.LBB0_423:
	ds_read_b32 v152, v163 offset:8
	v_lshl_add_u32 v150, s30, 8, v1
	v_cmp_lt_i32_e32 vcc, s67, v150
	s_and_saveexec_b64 s[30:31], vcc
	s_xor_b64 s[30:31], exec, s[30:31]
	v_add_u32_e32 v4, 0xffffc000, v150
	v_mov_b32_e32 v5, v2
	v_lshlrev_b64 v[4:5], 13, v[4:5]
	v_lshl_add_u64 v[154:155], s[38:39], 0, v[4:5]
	v_mov_b32_e32 v151, v2
	s_andn2_saveexec_b64 s[30:31], s[30:31]
	v_ashrrev_i32_e32 v151, 31, v150
	v_lshlrev_b64 v[4:5], 13, v[150:151]
	v_lshl_add_u64 v[154:155], s[36:37], 0, v[4:5]
	s_or_b64 exec, exec, s[30:31]
	v_lshl_or_b32 v4, s28, 8, v159
	v_ashrrev_i32_e32 v5, 31, v4
	v_lshl_add_u64 v[154:155], v[4:5], 2, v[154:155]
	global_load_dwordx4 v[164:167], v[154:155], off nt
	global_load_dwordx4 v[168:171], v[154:155], off offset:16 nt
	global_load_dwordx4 v[242:245], v[154:155], off offset:512 nt
	global_load_dwordx4 v[246:249], v[154:155], off offset:528 nt
	v_lshlrev_b64 v[172:173], 12, v[150:151]
	v_lshl_add_u64 v[172:173], s[16:17], 0, v[172:173]
	v_lshl_add_u64 v[172:173], v[4:5], 1, v[172:173]
	s_waitcnt vmcnt(2) lgkmcnt(0)
	v_pk_fma_f32 v[166:167], v[132:133], v[152:153], v[166:167] op_sel_hi:[1,0,1]
	v_pk_fma_f32 v[164:165], v[130:131], v[152:153], v[164:165] op_sel_hi:[1,0,1]
	v_pk_fma_f32 v[170:171], v[128:129], v[152:153], v[170:171] op_sel_hi:[1,0,1]
	v_pk_fma_f32 v[168:169], v[126:127], v[152:153], v[168:169] op_sel_hi:[1,0,1]
	v_cvt_pk_bf16_f32 v126, v164, v165
	v_cvt_pk_bf16_f32 v127, v166, v167
	v_mul_f32_e32 v153, v167, v167
	v_cvt_pk_bf16_f32 v128, v168, v169
	v_cvt_pk_bf16_f32 v129, v170, v171
	global_store_dwordx4 v[172:173], v[126:129], off
	s_nop 0
	s_nop 0
	s_nop 0
	v_fmac_f32_e32 v153, v166, v166
	v_mul_f32_e32 v3, v165, v165
	v_mul_f32_e32 v154, v169, v169
	v_fmac_f32_e32 v3, v164, v164
	v_mul_f32_e32 v155, v171, v171
	v_fmac_f32_e32 v154, v168, v168
	v_add_f32_e32 v3, v3, v153
	v_fmac_f32_e32 v155, v170, v170
	v_add_f32_e32 v3, v3, v154
	v_add_f32_e32 v3, v155, v3
	s_waitcnt vmcnt(2)
	v_pk_fma_f32 v[124:125], v[124:125], v[152:153], v[244:245] op_sel_hi:[1,0,1]
	v_pk_fma_f32 v[122:123], v[122:123], v[152:153], v[242:243] op_sel_hi:[1,0,1]
	s_waitcnt vmcnt(1)
	v_pk_fma_f32 v[128:129], v[118:119], v[152:153], v[246:247] op_sel_hi:[1,0,1]
	v_mul_f32_e32 v130, v123, v123
	v_mul_f32_e32 v131, v125, v125
	v_pk_fma_f32 v[126:127], v[120:121], v[152:153], v[248:249] op_sel_hi:[1,0,1]
	v_mul_f32_e32 v132, v129, v129
	v_cvt_pk_bf16_f32 v118, v122, v123
	v_fmac_f32_e32 v130, v122, v122
	v_fmac_f32_e32 v131, v124, v124
	v_mul_f32_e32 v133, v127, v127
	v_cvt_pk_bf16_f32 v119, v124, v125
	v_cvt_pk_bf16_f32 v120, v128, v129
	v_cvt_pk_bf16_f32 v121, v126, v127
	v_fmac_f32_e32 v132, v128, v128
	global_store_dwordx4 v[172:173], v[118:121], off offset:256
	v_fmac_f32_e32 v133, v126, v126
	s_nop 0
	v_add_f32_e32 v118, v130, v131
	v_add_f32_e32 v118, v118, v132
	v_add_f32_e32 v118, v133, v118
	v_add_f32_e32 v3, v3, v118
	v_mov_b32_e32 v118, v3
	s_nop 1
	v_permlane16_swap_b32_e32 v3, v118
	v_add_f32_e32 v3, v3, v118
	v_mov_b32_e32 v118, v3
	s_nop 1
	v_permlane32_swap_b32_e32 v3, v118
	v_add_f32_e32 v3, v3, v118
	v_mov_b32_e32 v226, v3
	v_lshl_add_u64 v[250:251], v[150:151], 2, s[18:19]
	ds_read_b32 v120, v163 offset:264
	v_or_b32_e32 v118, 16, v150
	v_cmp_lt_i32_e32 vcc, s67, v118
	s_and_saveexec_b64 s[28:29], vcc
	s_xor_b64 s[28:29], exec, s[28:29]
	v_add_u32_e32 v122, 0xffffc010, v150
	v_mov_b32_e32 v123, v2
	v_lshlrev_b64 v[122:123], 13, v[122:123]
	v_lshl_add_u64 v[122:123], s[38:39], 0, v[122:123]
	v_mov_b32_e32 v119, v2
	s_andn2_saveexec_b64 s[28:29], s[28:29]
	v_ashrrev_i32_e32 v119, 31, v118
	v_lshlrev_b64 v[122:123], 13, v[118:119]
	v_lshl_add_u64 v[122:123], s[36:37], 0, v[122:123]
	s_or_b64 exec, exec, s[28:29]
	v_lshl_add_u64 v[130:131], v[4:5], 2, v[122:123]
	global_load_dwordx4 v[122:125], v[130:131], off nt
	global_load_dwordx4 v[126:129], v[130:131], off offset:16 nt
	global_load_dwordx4 v[242:245], v[130:131], off offset:512 nt
	global_load_dwordx4 v[246:249], v[130:131], off offset:528 nt
	v_lshlrev_b64 v[132:133], 12, v[118:119]
	v_lshl_add_u64 v[132:133], s[16:17], 0, v[132:133]
	v_lshl_add_u64 v[132:133], v[4:5], 1, v[132:133]
	s_waitcnt vmcnt(3) lgkmcnt(0)
	v_pk_fma_f32 v[124:125], v[116:117], v[120:121], v[124:125] op_sel_hi:[1,0,1]
	v_pk_fma_f32 v[122:123], v[114:115], v[120:121], v[122:123] op_sel_hi:[1,0,1]
	s_waitcnt vmcnt(2)
	v_pk_fma_f32 v[128:129], v[112:113], v[120:121], v[128:129] op_sel_hi:[1,0,1]
	v_pk_fma_f32 v[126:127], v[110:111], v[120:121], v[126:127] op_sel_hi:[1,0,1]
	v_cvt_pk_bf16_f32 v110, v122, v123
	v_cvt_pk_bf16_f32 v111, v124, v125
	v_mul_f32_e32 v121, v125, v125
	v_cvt_pk_bf16_f32 v112, v126, v127
	v_cvt_pk_bf16_f32 v113, v128, v129
	global_store_dwordx4 v[132:133], v[110:113], off
	s_nop 0
	s_nop 0
	s_nop 0
	v_fmac_f32_e32 v121, v124, v124
	v_mul_f32_e32 v3, v123, v123
	v_mul_f32_e32 v123, v127, v127
	v_fmac_f32_e32 v3, v122, v122
	v_mul_f32_e32 v125, v129, v129
	v_fmac_f32_e32 v123, v126, v126
	v_add_f32_e32 v3, v3, v121
	v_fmac_f32_e32 v125, v128, v128
	v_add_f32_e32 v3, v3, v123
	v_add_f32_e32 v3, v125, v3
	s_waitcnt vmcnt(2)
	v_pk_fma_f32 v[108:109], v[108:109], v[120:121], v[244:245] op_sel_hi:[1,0,1]
	v_pk_fma_f32 v[106:107], v[106:107], v[120:121], v[242:243] op_sel_hi:[1,0,1]
	s_waitcnt vmcnt(1)
; __device__ __forceinline__ unsigned cvt_pk_bf16(float lo, float hi) { unsigned r; asm volatile("v_cvt_pk_bf16_f32 %0, %1, %2" : "=v"(r) : "v"(lo), "v"(hi)); return r; }
;     __device__ __forceinline__ void final(const f32x4 (&acc)[2][2][4][2], const Unit& u, int ui, int wr, int wc, int fr, int fq) const {
;         const int row0 = u.pm * BM + wr * 64 + fr, col0 = u.pn * BM + wc * 32 + 8 * fq;
; #pragma unroll
;         for (int ai = 0; ai < 2; ++ai)
; #pragma unroll
;             for (int m = 0; m < 4; ++m) { const int row = row0 + ai * HALF + m * 16; const float f = tab[(ui * 256 + ai * HALF + wr * 64 + m * 16 + fr) * 4 + 2];
;                 const float* src = (row < 16384 ? srcA + (size_t)row * 2048 : srcB + (size_t)(row - 16384) * 2048) + col0; float s = 0.f;
; #pragma unroll
;                 for (int bj = 0; bj < 2; ++bj) { const f32x4 v0 = acc[ai][bj][m][0] * f + __builtin_nontemporal_load((const f32x4*)(src + bj * HALF)), v1 = acc[ai][bj][m][1] * f + __builtin_nontemporal_load((const f32x4*)(src + bj * HALF + 4));
;                     s += (v0[0] * v0[0] + v0[1] * v0[1]) + (v0[2] * v0[2] + v0[3] * v0[3]) + (v1[0] * v1[0] + v1[1] * v1[1]) + (v1[2] * v1[2] + v1[3] * v1[3]);
;                     u32x4 w; w.x = cvt_pk_bf16(v0[0], v0[1]); w.y = cvt_pk_bf16(v0[2], v0[3]); w.z = cvt_pk_bf16(v1[0], v1[1]); w.w = cvt_pk_bf16(v1[2], v1[3]);
;                     *(u32x4*)(xb + (size_t)row * 2048 + col0 + bj * HALF) = w; }
;                 s = sum_x32(sum_x16(s)); asm volatile("" : "+v"(s));
;                 if (fq == 0) atomicAdd(ss + row, s); }
;     }
	v_pk_fma_f32 v[112:113], v[102:103], v[120:121], v[246:247] op_sel_hi:[1,0,1]
	v_mul_f32_e32 v114, v107, v107
	v_mul_f32_e32 v115, v109, v109
	v_pk_fma_f32 v[110:111], v[104:105], v[120:121], v[248:249] op_sel_hi:[1,0,1]
	v_mul_f32_e32 v116, v113, v113
	v_cvt_pk_bf16_f32 v102, v106, v107
	v_fmac_f32_e32 v114, v106, v106
	v_fmac_f32_e32 v115, v108, v108
	v_mul_f32_e32 v117, v111, v111
	v_cvt_pk_bf16_f32 v103, v108, v109
	v_cvt_pk_bf16_f32 v104, v112, v113
	v_cvt_pk_bf16_f32 v105, v110, v111
	v_fmac_f32_e32 v116, v112, v112
	global_store_dwordx4 v[132:133], v[102:105], off offset:256
	v_fmac_f32_e32 v117, v110, v110
	s_nop 0
	v_add_f32_e32 v102, v114, v115
	v_add_f32_e32 v102, v102, v116
	v_add_f32_e32 v102, v117, v102
	v_add_f32_e32 v3, v3, v102
	v_mov_b32_e32 v102, v3
	s_nop 1
	v_permlane16_swap_b32_e32 v3, v102
	v_add_f32_e32 v3, v3, v102
	v_mov_b32_e32 v102, v3
	s_nop 1
	v_permlane32_swap_b32_e32 v3, v102
	v_add_f32_e32 v3, v3, v102
	v_mov_b32_e32 v227, v3
	ds_read_b32 v104, v163 offset:520
	v_or_b32_e32 v102, 32, v150
	v_cmp_lt_i32_e32 vcc, s67, v102
	s_and_saveexec_b64 s[28:29], vcc
	s_xor_b64 s[28:29], exec, s[28:29]
	v_add_u32_e32 v106, 0xffffc020, v150
	v_mov_b32_e32 v107, v2
	v_lshlrev_b64 v[106:107], 13, v[106:107]
	v_lshl_add_u64 v[106:107], s[38:39], 0, v[106:107]
	v_mov_b32_e32 v103, v2
	s_andn2_saveexec_b64 s[28:29], s[28:29]
	v_ashrrev_i32_e32 v103, 31, v102
	v_lshlrev_b64 v[106:107], 13, v[102:103]
	v_lshl_add_u64 v[106:107], s[36:37], 0, v[106:107]
	s_or_b64 exec, exec, s[28:29]
	v_lshl_add_u64 v[114:115], v[4:5], 2, v[106:107]
	global_load_dwordx4 v[106:109], v[114:115], off nt
	global_load_dwordx4 v[110:113], v[114:115], off offset:16 nt
	global_load_dwordx4 v[242:245], v[114:115], off offset:512 nt
	global_load_dwordx4 v[246:249], v[114:115], off offset:528 nt
	v_lshlrev_b64 v[116:117], 12, v[102:103]
	v_lshl_add_u64 v[116:117], s[16:17], 0, v[116:117]
	v_lshl_add_u64 v[116:117], v[4:5], 1, v[116:117]
	s_waitcnt vmcnt(3) lgkmcnt(0)
	v_pk_fma_f32 v[108:109], v[100:101], v[104:105], v[108:109] op_sel_hi:[1,0,1]
	v_pk_fma_f32 v[106:107], v[98:99], v[104:105], v[106:107] op_sel_hi:[1,0,1]
	s_waitcnt vmcnt(2)
	v_pk_fma_f32 v[112:113], v[96:97], v[104:105], v[112:113] op_sel_hi:[1,0,1]
	v_pk_fma_f32 v[110:111], v[94:95], v[104:105], v[110:111] op_sel_hi:[1,0,1]
	v_cvt_pk_bf16_f32 v94, v106, v107
	v_cvt_pk_bf16_f32 v95, v108, v109
	v_mul_f32_e32 v105, v109, v109
	v_cvt_pk_bf16_f32 v96, v110, v111
	v_cvt_pk_bf16_f32 v97, v112, v113
	global_store_dwordx4 v[116:117], v[94:97], off
	s_nop 0
	s_nop 0
	s_nop 0
	v_fmac_f32_e32 v105, v108, v108
	v_mul_f32_e32 v3, v107, v107
	v_mul_f32_e32 v107, v111, v111
	v_fmac_f32_e32 v3, v106, v106
	v_mul_f32_e32 v109, v113, v113
	v_fmac_f32_e32 v107, v110, v110
	v_add_f32_e32 v3, v3, v105
	v_fmac_f32_e32 v109, v112, v112
	v_add_f32_e32 v3, v3, v107
	v_add_f32_e32 v3, v109, v3
	s_waitcnt vmcnt(2)
	v_pk_fma_f32 v[92:93], v[92:93], v[104:105], v[244:245] op_sel_hi:[1,0,1]
	v_pk_fma_f32 v[90:91], v[90:91], v[104:105], v[242:243] op_sel_hi:[1,0,1]
	s_waitcnt vmcnt(1)
	v_pk_fma_f32 v[96:97], v[86:87], v[104:105], v[246:247] op_sel_hi:[1,0,1]
	v_mul_f32_e32 v98, v91, v91
	v_mul_f32_e32 v99, v93, v93
	v_pk_fma_f32 v[94:95], v[88:89], v[104:105], v[248:249] op_sel_hi:[1,0,1]
	v_mul_f32_e32 v100, v97, v97
	v_cvt_pk_bf16_f32 v86, v90, v91
	v_fmac_f32_e32 v98, v90, v90
	v_fmac_f32_e32 v99, v92, v92
	v_mul_f32_e32 v101, v95, v95
	v_cvt_pk_bf16_f32 v87, v92, v93
	v_cvt_pk_bf16_f32 v88, v96, v97
	v_cvt_pk_bf16_f32 v89, v94, v95
	v_fmac_f32_e32 v100, v96, v96
	global_store_dwordx4 v[116:117], v[86:89], off offset:256
	v_fmac_f32_e32 v101, v94, v94
	s_nop 0
	v_add_f32_e32 v86, v98, v99
	v_add_f32_e32 v86, v86, v100
	v_add_f32_e32 v86, v101, v86
	v_add_f32_e32 v3, v3, v86
	v_mov_b32_e32 v86, v3
	s_nop 1
	v_permlane16_swap_b32_e32 v3, v86
	v_add_f32_e32 v3, v3, v86
	v_mov_b32_e32 v86, v3
	s_nop 1
	v_permlane32_swap_b32_e32 v3, v86
	v_add_f32_e32 v3, v3, v86
	v_mov_b32_e32 v228, v3
	ds_read_b32 v88, v163 offset:776
	v_or_b32_e32 v86, 48, v150
	v_cmp_lt_i32_e32 vcc, s67, v86
	s_and_saveexec_b64 s[28:29], vcc
	s_xor_b64 s[28:29], exec, s[28:29]
	v_add_u32_e32 v90, 0xffffc030, v150
	v_mov_b32_e32 v91, v2
	v_lshlrev_b64 v[90:91], 13, v[90:91]
	v_lshl_add_u64 v[90:91], s[38:39], 0, v[90:91]
	v_mov_b32_e32 v87, v2
	s_andn2_saveexec_b64 s[28:29], s[28:29]
	v_ashrrev_i32_e32 v87, 31, v86
	v_lshlrev_b64 v[90:91], 13, v[86:87]
	v_lshl_add_u64 v[90:91], s[36:37], 0, v[90:91]
	s_or_b64 exec, exec, s[28:29]
	v_lshl_add_u64 v[98:99], v[4:5], 2, v[90:91]
	global_load_dwordx4 v[90:93], v[98:99], off nt
	global_load_dwordx4 v[94:97], v[98:99], off offset:16 nt
	global_load_dwordx4 v[242:245], v[98:99], off offset:512 nt
	global_load_dwordx4 v[246:249], v[98:99], off offset:528 nt
	v_lshlrev_b64 v[100:101], 12, v[86:87]
	v_lshl_add_u64 v[100:101], s[16:17], 0, v[100:101]
	v_lshl_add_u64 v[100:101], v[4:5], 1, v[100:101]
	s_waitcnt vmcnt(3) lgkmcnt(0)
	v_pk_fma_f32 v[92:93], v[84:85], v[88:89], v[92:93] op_sel_hi:[1,0,1]
	v_pk_fma_f32 v[90:91], v[82:83], v[88:89], v[90:91] op_sel_hi:[1,0,1]
	s_waitcnt vmcnt(2)
	v_pk_fma_f32 v[96:97], v[80:81], v[88:89], v[96:97] op_sel_hi:[1,0,1]
	v_pk_fma_f32 v[94:95], v[78:79], v[88:89], v[94:95] op_sel_hi:[1,0,1]
	v_cvt_pk_bf16_f32 v78, v90, v91
	v_cvt_pk_bf16_f32 v79, v92, v93
	v_mul_f32_e32 v89, v93, v93
	v_cvt_pk_bf16_f32 v80, v94, v95
	v_cvt_pk_bf16_f32 v81, v96, v97
	global_store_dwordx4 v[100:101], v[78:81], off
	s_nop 0
	s_nop 0
	s_nop 0
	v_fmac_f32_e32 v89, v92, v92
	v_mul_f32_e32 v3, v91, v91
	v_mul_f32_e32 v91, v95, v95
	v_fmac_f32_e32 v3, v90, v90
	v_mul_f32_e32 v93, v97, v97
	v_fmac_f32_e32 v91, v94, v94
	v_add_f32_e32 v3, v3, v89
	v_fmac_f32_e32 v93, v96, v96
	v_add_f32_e32 v3, v3, v91
	v_add_f32_e32 v3, v93, v3
	s_waitcnt vmcnt(2)
; __device__ __forceinline__ unsigned cvt_pk_bf16(float lo, float hi) { unsigned r; asm volatile("v_cvt_pk_bf16_f32 %0, %1, %2" : "=v"(r) : "v"(lo), "v"(hi)); return r; }
;     __device__ __forceinline__ void final(const f32x4 (&acc)[2][2][4][2], const Unit& u, int ui, int wr, int wc, int fr, int fq) const {
;         const int row0 = u.pm * BM + wr * 64 + fr, col0 = u.pn * BM + wc * 32 + 8 * fq;
; #pragma unroll
;         for (int ai = 0; ai < 2; ++ai)
; #pragma unroll
;             for (int m = 0; m < 4; ++m) { const int row = row0 + ai * HALF + m * 16; const float f = tab[(ui * 256 + ai * HALF + wr * 64 + m * 16 + fr) * 4 + 2];
;                 const float* src = (row < 16384 ? srcA + (size_t)row * 2048 : srcB + (size_t)(row - 16384) * 2048) + col0; float s = 0.f;
; #pragma unroll
;                 for (int bj = 0; bj < 2; ++bj) { const f32x4 v0 = acc[ai][bj][m][0] * f + __builtin_nontemporal_load((const f32x4*)(src + bj * HALF)), v1 = acc[ai][bj][m][1] * f + __builtin_nontemporal_load((const f32x4*)(src + bj * HALF + 4));
;                     s += (v0[0] * v0[0] + v0[1] * v0[1]) + (v0[2] * v0[2] + v0[3] * v0[3]) + (v1[0] * v1[0] + v1[1] * v1[1]) + (v1[2] * v1[2] + v1[3] * v1[3]);
;                     u32x4 w; w.x = cvt_pk_bf16(v0[0], v0[1]); w.y = cvt_pk_bf16(v0[2], v0[3]); w.z = cvt_pk_bf16(v1[0], v1[1]); w.w = cvt_pk_bf16(v1[2], v1[3]);
;                     *(u32x4*)(xb + (size_t)row * 2048 + col0 + bj * HALF) = w; }
;                 s = sum_x32(sum_x16(s)); asm volatile("" : "+v"(s));
;                 if (fq == 0) atomicAdd(ss + row, s); }
;     }
	v_pk_fma_f32 v[76:77], v[76:77], v[88:89], v[244:245] op_sel_hi:[1,0,1]
	v_pk_fma_f32 v[74:75], v[74:75], v[88:89], v[242:243] op_sel_hi:[1,0,1]
	s_waitcnt vmcnt(1)
	v_pk_fma_f32 v[80:81], v[70:71], v[88:89], v[246:247] op_sel_hi:[1,0,1]
	v_mul_f32_e32 v82, v75, v75
	v_mul_f32_e32 v83, v77, v77
	v_pk_fma_f32 v[78:79], v[72:73], v[88:89], v[248:249] op_sel_hi:[1,0,1]
	v_mul_f32_e32 v84, v81, v81
	v_cvt_pk_bf16_f32 v70, v74, v75
	v_fmac_f32_e32 v82, v74, v74
	v_fmac_f32_e32 v83, v76, v76
	v_mul_f32_e32 v85, v79, v79
	v_cvt_pk_bf16_f32 v71, v76, v77
	v_cvt_pk_bf16_f32 v72, v80, v81
	v_cvt_pk_bf16_f32 v73, v78, v79
	v_fmac_f32_e32 v84, v80, v80
	global_store_dwordx4 v[100:101], v[70:73], off offset:256
	v_fmac_f32_e32 v85, v78, v78
	s_nop 0
	v_add_f32_e32 v70, v82, v83
	v_add_f32_e32 v70, v70, v84
	v_add_f32_e32 v70, v85, v70
	v_add_f32_e32 v3, v3, v70
	v_mov_b32_e32 v70, v3
	s_nop 1
	v_permlane16_swap_b32_e32 v3, v70
	v_add_f32_e32 v3, v3, v70
	v_mov_b32_e32 v70, v3
	s_nop 1
	v_permlane32_swap_b32_e32 v3, v70
	v_add_f32_e32 v3, v3, v70
	v_mov_b32_e32 v229, v3
	ds_read_b32 v72, v163 offset:2056
	v_add_u32_e32 v70, 0x80, v150
	v_cmp_lt_i32_e32 vcc, s80, v150
	s_and_saveexec_b64 s[28:29], vcc
	s_xor_b64 s[28:29], exec, s[28:29]
	v_add_u32_e32 v74, 0xffffc080, v150
	v_mov_b32_e32 v75, v2
	v_lshlrev_b64 v[74:75], 13, v[74:75]
	v_lshl_add_u64 v[74:75], s[38:39], 0, v[74:75]
	v_mov_b32_e32 v71, v2
	s_andn2_saveexec_b64 s[28:29], s[28:29]
	v_ashrrev_i32_e32 v71, 31, v70
	v_lshlrev_b64 v[74:75], 13, v[70:71]
	v_lshl_add_u64 v[74:75], s[36:37], 0, v[74:75]
	s_or_b64 exec, exec, s[28:29]
	v_lshl_add_u64 v[82:83], v[4:5], 2, v[74:75]
	global_load_dwordx4 v[74:77], v[82:83], off nt
	global_load_dwordx4 v[78:81], v[82:83], off offset:16 nt
	global_load_dwordx4 v[242:245], v[82:83], off offset:512 nt
	global_load_dwordx4 v[246:249], v[82:83], off offset:528 nt
	v_lshlrev_b64 v[84:85], 12, v[70:71]
	v_lshl_add_u64 v[84:85], s[16:17], 0, v[84:85]
	v_lshl_add_u64 v[84:85], v[4:5], 1, v[84:85]
	s_waitcnt vmcnt(3) lgkmcnt(0)
	v_pk_fma_f32 v[76:77], v[68:69], v[72:73], v[76:77] op_sel_hi:[1,0,1]
	v_pk_fma_f32 v[74:75], v[66:67], v[72:73], v[74:75] op_sel_hi:[1,0,1]
	s_waitcnt vmcnt(2)
	v_pk_fma_f32 v[80:81], v[64:65], v[72:73], v[80:81] op_sel_hi:[1,0,1]
	v_pk_fma_f32 v[78:79], v[62:63], v[72:73], v[78:79] op_sel_hi:[1,0,1]
	v_cvt_pk_bf16_f32 v62, v74, v75
	v_cvt_pk_bf16_f32 v63, v76, v77
	v_mul_f32_e32 v73, v77, v77
	v_cvt_pk_bf16_f32 v64, v78, v79
	v_cvt_pk_bf16_f32 v65, v80, v81
	global_store_dwordx4 v[84:85], v[62:65], off
	s_nop 0
	s_nop 0
	s_nop 0
	v_fmac_f32_e32 v73, v76, v76
	v_mul_f32_e32 v3, v75, v75
	v_mul_f32_e32 v75, v79, v79
	v_fmac_f32_e32 v3, v74, v74
	v_mul_f32_e32 v77, v81, v81
	v_fmac_f32_e32 v75, v78, v78
	v_add_f32_e32 v3, v3, v73
	v_fmac_f32_e32 v77, v80, v80
	v_add_f32_e32 v3, v3, v75
	v_add_f32_e32 v3, v77, v3
	s_waitcnt vmcnt(2)
	v_pk_fma_f32 v[60:61], v[60:61], v[72:73], v[244:245] op_sel_hi:[1,0,1]
	v_pk_fma_f32 v[58:59], v[58:59], v[72:73], v[242:243] op_sel_hi:[1,0,1]
	s_waitcnt vmcnt(1)
	v_pk_fma_f32 v[64:65], v[54:55], v[72:73], v[246:247] op_sel_hi:[1,0,1]
	v_mul_f32_e32 v66, v59, v59
	v_mul_f32_e32 v67, v61, v61
	v_pk_fma_f32 v[62:63], v[56:57], v[72:73], v[248:249] op_sel_hi:[1,0,1]
	v_mul_f32_e32 v68, v65, v65
	v_cvt_pk_bf16_f32 v54, v58, v59
	v_fmac_f32_e32 v66, v58, v58
	v_fmac_f32_e32 v67, v60, v60
	v_mul_f32_e32 v69, v63, v63
	v_cvt_pk_bf16_f32 v55, v60, v61
	v_cvt_pk_bf16_f32 v56, v64, v65
	v_cvt_pk_bf16_f32 v57, v62, v63
	v_fmac_f32_e32 v68, v64, v64
	global_store_dwordx4 v[84:85], v[54:57], off offset:256
	v_fmac_f32_e32 v69, v62, v62
	s_nop 0
	v_add_f32_e32 v54, v66, v67
	v_add_f32_e32 v54, v54, v68
	v_add_f32_e32 v54, v69, v54
	v_add_f32_e32 v3, v3, v54
	v_mov_b32_e32 v54, v3
	s_nop 1
	v_permlane16_swap_b32_e32 v3, v54
	v_add_f32_e32 v3, v3, v54
	v_mov_b32_e32 v54, v3
	s_nop 1
	v_permlane32_swap_b32_e32 v3, v54
	v_add_f32_e32 v3, v3, v54
	v_mov_b32_e32 v230, v3
	ds_read_b32 v56, v163 offset:2312
	v_add_u32_e32 v54, 0x90, v150
	v_cmp_lt_i32_e32 vcc, s81, v150
	s_and_saveexec_b64 s[28:29], vcc
	s_xor_b64 s[28:29], exec, s[28:29]
	v_add_u32_e32 v58, 0xffffc090, v150
	v_mov_b32_e32 v59, v2
	v_lshlrev_b64 v[58:59], 13, v[58:59]
	v_lshl_add_u64 v[58:59], s[38:39], 0, v[58:59]
	v_mov_b32_e32 v55, v2
	s_andn2_saveexec_b64 s[28:29], s[28:29]
	v_ashrrev_i32_e32 v55, 31, v54
	v_lshlrev_b64 v[58:59], 13, v[54:55]
	v_lshl_add_u64 v[58:59], s[36:37], 0, v[58:59]
	s_or_b64 exec, exec, s[28:29]
	v_lshl_add_u64 v[66:67], v[4:5], 2, v[58:59]
	global_load_dwordx4 v[58:61], v[66:67], off nt
	global_load_dwordx4 v[62:65], v[66:67], off offset:16 nt
	global_load_dwordx4 v[242:245], v[66:67], off offset:512 nt
	global_load_dwordx4 v[246:249], v[66:67], off offset:528 nt
	v_lshlrev_b64 v[68:69], 12, v[54:55]
	v_lshl_add_u64 v[68:69], s[16:17], 0, v[68:69]
	v_lshl_add_u64 v[68:69], v[4:5], 1, v[68:69]
	s_waitcnt vmcnt(3) lgkmcnt(0)
	v_pk_fma_f32 v[60:61], v[52:53], v[56:57], v[60:61] op_sel_hi:[1,0,1]
	v_pk_fma_f32 v[58:59], v[50:51], v[56:57], v[58:59] op_sel_hi:[1,0,1]
	s_waitcnt vmcnt(2)
	v_pk_fma_f32 v[64:65], v[48:49], v[56:57], v[64:65] op_sel_hi:[1,0,1]
	v_pk_fma_f32 v[62:63], v[46:47], v[56:57], v[62:63] op_sel_hi:[1,0,1]
	v_cvt_pk_bf16_f32 v46, v58, v59
	v_cvt_pk_bf16_f32 v47, v60, v61
	v_mul_f32_e32 v57, v61, v61
	v_cvt_pk_bf16_f32 v48, v62, v63
	v_cvt_pk_bf16_f32 v49, v64, v65
	global_store_dwordx4 v[68:69], v[46:49], off
	s_nop 0
	s_nop 0
	s_nop 0
	v_fmac_f32_e32 v57, v60, v60
	v_mul_f32_e32 v3, v59, v59
	v_mul_f32_e32 v59, v63, v63
	v_fmac_f32_e32 v3, v58, v58
	v_mul_f32_e32 v61, v65, v65
	v_fmac_f32_e32 v59, v62, v62
	v_add_f32_e32 v3, v3, v57
	v_fmac_f32_e32 v61, v64, v64
	v_add_f32_e32 v3, v3, v59
	v_add_f32_e32 v3, v61, v3
	s_waitcnt vmcnt(2)
; __device__ __forceinline__ unsigned cvt_pk_bf16(float lo, float hi) { unsigned r; asm volatile("v_cvt_pk_bf16_f32 %0, %1, %2" : "=v"(r) : "v"(lo), "v"(hi)); return r; }
;     __device__ __forceinline__ void final(const f32x4 (&acc)[2][2][4][2], const Unit& u, int ui, int wr, int wc, int fr, int fq) const {
;         const int row0 = u.pm * BM + wr * 64 + fr, col0 = u.pn * BM + wc * 32 + 8 * fq;
; #pragma unroll
;         for (int ai = 0; ai < 2; ++ai)
; #pragma unroll
;             for (int m = 0; m < 4; ++m) { const int row = row0 + ai * HALF + m * 16; const float f = tab[(ui * 256 + ai * HALF + wr * 64 + m * 16 + fr) * 4 + 2];
;                 const float* src = (row < 16384 ? srcA + (size_t)row * 2048 : srcB + (size_t)(row - 16384) * 2048) + col0; float s = 0.f;
; #pragma unroll
;                 for (int bj = 0; bj < 2; ++bj) { const f32x4 v0 = acc[ai][bj][m][0] * f + __builtin_nontemporal_load((const f32x4*)(src + bj * HALF)), v1 = acc[ai][bj][m][1] * f + __builtin_nontemporal_load((const f32x4*)(src + bj * HALF + 4));
;                     s += (v0[0] * v0[0] + v0[1] * v0[1]) + (v0[2] * v0[2] + v0[3] * v0[3]) + (v1[0] * v1[0] + v1[1] * v1[1]) + (v1[2] * v1[2] + v1[3] * v1[3]);
;                     u32x4 w; w.x = cvt_pk_bf16(v0[0], v0[1]); w.y = cvt_pk_bf16(v0[2], v0[3]); w.z = cvt_pk_bf16(v1[0], v1[1]); w.w = cvt_pk_bf16(v1[2], v1[3]);
;                     *(u32x4*)(xb + (size_t)row * 2048 + col0 + bj * HALF) = w; }
;                 s = sum_x32(sum_x16(s)); asm volatile("" : "+v"(s));
;                 if (fq == 0) atomicAdd(ss + row, s); }
;     }
	v_pk_fma_f32 v[44:45], v[44:45], v[56:57], v[244:245] op_sel_hi:[1,0,1]
	v_pk_fma_f32 v[42:43], v[42:43], v[56:57], v[242:243] op_sel_hi:[1,0,1]
	s_waitcnt vmcnt(1)
	v_pk_fma_f32 v[48:49], v[38:39], v[56:57], v[246:247] op_sel_hi:[1,0,1]
	v_mul_f32_e32 v50, v43, v43
	v_mul_f32_e32 v51, v45, v45
	v_pk_fma_f32 v[46:47], v[40:41], v[56:57], v[248:249] op_sel_hi:[1,0,1]
	v_mul_f32_e32 v52, v49, v49
	v_cvt_pk_bf16_f32 v38, v42, v43
	v_fmac_f32_e32 v50, v42, v42
	v_fmac_f32_e32 v51, v44, v44
	v_mul_f32_e32 v53, v47, v47
	v_cvt_pk_bf16_f32 v39, v44, v45
	v_cvt_pk_bf16_f32 v40, v48, v49
	v_cvt_pk_bf16_f32 v41, v46, v47
	v_fmac_f32_e32 v52, v48, v48
	global_store_dwordx4 v[68:69], v[38:41], off offset:256
	v_fmac_f32_e32 v53, v46, v46
	s_nop 0
	v_add_f32_e32 v38, v50, v51
	v_add_f32_e32 v38, v38, v52
	v_add_f32_e32 v38, v53, v38
	v_add_f32_e32 v3, v3, v38
	v_mov_b32_e32 v38, v3
	s_nop 1
	v_permlane16_swap_b32_e32 v3, v38
	v_add_f32_e32 v3, v3, v38
	v_mov_b32_e32 v38, v3
	s_nop 1
	v_permlane32_swap_b32_e32 v3, v38
	v_add_f32_e32 v3, v3, v38
	v_mov_b32_e32 v231, v3
	ds_read_b32 v40, v163 offset:2568
	v_add_u32_e32 v38, 0xa0, v150
	v_cmp_lt_i32_e32 vcc, s82, v150
	s_and_saveexec_b64 s[28:29], vcc
	s_xor_b64 s[28:29], exec, s[28:29]
	v_add_u32_e32 v42, 0xffffc0a0, v150
	v_mov_b32_e32 v43, v2
	v_lshlrev_b64 v[42:43], 13, v[42:43]
	v_lshl_add_u64 v[42:43], s[38:39], 0, v[42:43]
	v_mov_b32_e32 v39, v2
	s_andn2_saveexec_b64 s[28:29], s[28:29]
	v_ashrrev_i32_e32 v39, 31, v38
	v_lshlrev_b64 v[42:43], 13, v[38:39]
	v_lshl_add_u64 v[42:43], s[36:37], 0, v[42:43]
	s_or_b64 exec, exec, s[28:29]
	v_lshl_add_u64 v[50:51], v[4:5], 2, v[42:43]
	global_load_dwordx4 v[42:45], v[50:51], off nt
	global_load_dwordx4 v[46:49], v[50:51], off offset:16 nt
	global_load_dwordx4 v[242:245], v[50:51], off offset:512 nt
	global_load_dwordx4 v[246:249], v[50:51], off offset:528 nt
	v_lshlrev_b64 v[52:53], 12, v[38:39]
	v_lshl_add_u64 v[52:53], s[16:17], 0, v[52:53]
	v_lshl_add_u64 v[52:53], v[4:5], 1, v[52:53]
	s_waitcnt vmcnt(3) lgkmcnt(0)
	v_pk_fma_f32 v[44:45], v[36:37], v[40:41], v[44:45] op_sel_hi:[1,0,1]
	v_pk_fma_f32 v[42:43], v[34:35], v[40:41], v[42:43] op_sel_hi:[1,0,1]
	s_waitcnt vmcnt(2)
	v_pk_fma_f32 v[48:49], v[32:33], v[40:41], v[48:49] op_sel_hi:[1,0,1]
	v_pk_fma_f32 v[46:47], v[30:31], v[40:41], v[46:47] op_sel_hi:[1,0,1]
	v_cvt_pk_bf16_f32 v30, v42, v43
	v_cvt_pk_bf16_f32 v31, v44, v45
	v_mul_f32_e32 v41, v45, v45
	v_cvt_pk_bf16_f32 v32, v46, v47
	v_cvt_pk_bf16_f32 v33, v48, v49
	global_store_dwordx4 v[52:53], v[30:33], off
	s_nop 0
	s_nop 0
	s_nop 0
	v_fmac_f32_e32 v41, v44, v44
	v_mul_f32_e32 v3, v43, v43
	v_mul_f32_e32 v43, v47, v47
	v_fmac_f32_e32 v3, v42, v42
	v_mul_f32_e32 v45, v49, v49
	v_fmac_f32_e32 v43, v46, v46
	v_add_f32_e32 v3, v3, v41
	v_fmac_f32_e32 v45, v48, v48
	v_add_f32_e32 v3, v3, v43
	v_add_f32_e32 v3, v45, v3
	s_waitcnt vmcnt(2)
	v_pk_fma_f32 v[28:29], v[28:29], v[40:41], v[244:245] op_sel_hi:[1,0,1]
	v_pk_fma_f32 v[26:27], v[26:27], v[40:41], v[242:243] op_sel_hi:[1,0,1]
	s_waitcnt vmcnt(1)
; __device__ __forceinline__ unsigned cvt_pk_bf16(float lo, float hi) { unsigned r; asm volatile("v_cvt_pk_bf16_f32 %0, %1, %2" : "=v"(r) : "v"(lo), "v"(hi)); return r; }
; template <class Epi, class Sched, bool ALIGN_EPI = false, bool SP2 = false, bool KSEG = false>
; __device__ __forceinline__ void gemm_phase(PG8_LAS unsigned char* lds, const Gemm g, const Sched& S, const Epi& E) {
;     ...
;         if constexpr (!Epi::AFTER_DRAIN) { if constexpr (KSEG) E.final(acc, cur, ui, wr, wc, fr, fq); else E(acc, cur, wr, wc, fr, fq); S.done(cur); }
;         if (!has_next) break;
;     __device__ __forceinline__ void final(const f32x4 (&acc)[2][2][4][2], const Unit& u, int ui, int wr, int wc, int fr, int fq) const {
;         const int row0 = u.pm * BM + wr * 64 + fr, col0 = u.pn * BM + wc * 32 + 8 * fq;
; #pragma unroll
;         for (int ai = 0; ai < 2; ++ai)
; #pragma unroll
;             for (int m = 0; m < 4; ++m) { const int row = row0 + ai * HALF + m * 16; const float f = tab[(ui * 256 + ai * HALF + wr * 64 + m * 16 + fr) * 4 + 2];
;                 const float* src = (row < 16384 ? srcA + (size_t)row * 2048 : srcB + (size_t)(row - 16384) * 2048) + col0; float s = 0.f;
; #pragma unroll
;                 for (int bj = 0; bj < 2; ++bj) { const f32x4 v0 = acc[ai][bj][m][0] * f + __builtin_nontemporal_load((const f32x4*)(src + bj * HALF)), v1 = acc[ai][bj][m][1] * f + __builtin_nontemporal_load((const f32x4*)(src + bj * HALF + 4));
;                     s += (v0[0] * v0[0] + v0[1] * v0[1]) + (v0[2] * v0[2] + v0[3] * v0[3]) + (v1[0] * v1[0] + v1[1] * v1[1]) + (v1[2] * v1[2] + v1[3] * v1[3]);
;                     u32x4 w; w.x = cvt_pk_bf16(v0[0], v0[1]); w.y = cvt_pk_bf16(v0[2], v0[3]); w.z = cvt_pk_bf16(v1[0], v1[1]); w.w = cvt_pk_bf16(v1[2], v1[3]);
;                     *(u32x4*)(xb + (size_t)row * 2048 + col0 + bj * HALF) = w; }
;                 s = sum_x32(sum_x16(s)); asm volatile("" : "+v"(s));
;                 if (fq == 0) atomicAdd(ss + row, s); }
;     }
	v_pk_fma_f32 v[32:33], v[22:23], v[40:41], v[246:247] op_sel_hi:[1,0,1]
	v_mul_f32_e32 v34, v27, v27
	v_mul_f32_e32 v35, v29, v29
	v_pk_fma_f32 v[30:31], v[24:25], v[40:41], v[248:249] op_sel_hi:[1,0,1]
	v_mul_f32_e32 v36, v33, v33
	v_cvt_pk_bf16_f32 v22, v26, v27
	v_fmac_f32_e32 v34, v26, v26
	v_fmac_f32_e32 v35, v28, v28
	v_mul_f32_e32 v37, v31, v31
	v_cvt_pk_bf16_f32 v23, v28, v29
	v_cvt_pk_bf16_f32 v24, v32, v33
	v_cvt_pk_bf16_f32 v25, v30, v31
	v_fmac_f32_e32 v36, v32, v32
	global_store_dwordx4 v[52:53], v[22:25], off offset:256
	v_fmac_f32_e32 v37, v30, v30
	s_nop 0
	v_add_f32_e32 v22, v34, v35
	v_add_f32_e32 v22, v22, v36
	v_add_f32_e32 v22, v37, v22
	v_add_f32_e32 v3, v3, v22
	v_mov_b32_e32 v22, v3
	s_nop 1
	v_permlane16_swap_b32_e32 v3, v22
	v_add_f32_e32 v3, v3, v22
	v_mov_b32_e32 v22, v3
	s_nop 1
	v_permlane32_swap_b32_e32 v3, v22
	v_add_f32_e32 v3, v3, v22
	v_mov_b32_e32 v232, v3
	ds_read_b32 v24, v163 offset:2824
	v_add_u32_e32 v22, 0xb0, v150
	v_cmp_lt_i32_e32 vcc, s83, v150
	s_and_saveexec_b64 s[28:29], vcc
	s_xor_b64 s[28:29], exec, s[28:29]
	v_add_u32_e32 v26, 0xffffc0b0, v150
	v_mov_b32_e32 v27, v2
	v_lshlrev_b64 v[26:27], 13, v[26:27]
	v_lshl_add_u64 v[26:27], s[38:39], 0, v[26:27]
	v_mov_b32_e32 v23, v2
	s_andn2_saveexec_b64 s[28:29], s[28:29]
	v_ashrrev_i32_e32 v23, 31, v22
	v_lshlrev_b64 v[26:27], 13, v[22:23]
	v_lshl_add_u64 v[26:27], s[36:37], 0, v[26:27]
	s_or_b64 exec, exec, s[28:29]
	v_lshl_add_u64 v[34:35], v[4:5], 2, v[26:27]
	global_load_dwordx4 v[26:29], v[34:35], off nt
	global_load_dwordx4 v[30:33], v[34:35], off offset:16 nt
	global_load_dwordx4 v[242:245], v[34:35], off offset:512 nt
	global_load_dwordx4 v[246:249], v[34:35], off offset:528 nt
	v_lshlrev_b64 v[36:37], 12, v[22:23]
	v_lshl_add_u64 v[36:37], s[16:17], 0, v[36:37]
	v_lshl_add_u64 v[36:37], v[4:5], 1, v[36:37]
	s_waitcnt vmcnt(3) lgkmcnt(0)
	v_pk_fma_f32 v[4:5], v[20:21], v[24:25], v[28:29] op_sel_hi:[1,0,1]
	v_pk_fma_f32 v[26:27], v[18:19], v[24:25], v[26:27] op_sel_hi:[1,0,1]
	s_waitcnt vmcnt(2)
	v_pk_fma_f32 v[28:29], v[16:17], v[24:25], v[32:33] op_sel_hi:[1,0,1]
	v_pk_fma_f32 v[30:31], v[14:15], v[24:25], v[30:31] op_sel_hi:[1,0,1]
	v_cvt_pk_bf16_f32 v14, v26, v27
	v_cvt_pk_bf16_f32 v15, v4, v5
	v_mul_f32_e32 v3, v27, v27
	v_cvt_pk_bf16_f32 v16, v30, v31
	v_cvt_pk_bf16_f32 v17, v28, v29
	global_store_dwordx4 v[36:37], v[14:17], off
	s_nop 0
	s_nop 0
	s_nop 0
	v_mul_f32_e32 v25, v31, v31
	v_fmac_f32_e32 v25, v30, v30
	v_mul_f32_e32 v5, v5, v5
	v_fmac_f32_e32 v3, v26, v26
	v_fmac_f32_e32 v5, v4, v4
	v_mul_f32_e32 v27, v29, v29
	v_add_f32_e32 v3, v3, v5
	v_fmac_f32_e32 v27, v28, v28
	v_add_f32_e32 v3, v3, v25
	v_add_f32_e32 v3, v27, v3
	s_waitcnt vmcnt(2)
	v_pk_fma_f32 v[12:13], v[12:13], v[24:25], v[244:245] op_sel_hi:[1,0,1]
	v_pk_fma_f32 v[10:11], v[10:11], v[24:25], v[242:243] op_sel_hi:[1,0,1]
	s_waitcnt vmcnt(1)
	v_pk_fma_f32 v[14:15], v[6:7], v[24:25], v[246:247] op_sel_hi:[1,0,1]
	v_mul_f32_e32 v16, v11, v11
	v_mul_f32_e32 v17, v13, v13
	v_pk_fma_f32 v[8:9], v[8:9], v[24:25], v[248:249] op_sel_hi:[1,0,1]
	v_mul_f32_e32 v18, v15, v15
	v_cvt_pk_bf16_f32 v4, v10, v11
	v_fmac_f32_e32 v16, v10, v10
	v_fmac_f32_e32 v17, v12, v12
	v_mul_f32_e32 v19, v9, v9
	v_cvt_pk_bf16_f32 v5, v12, v13
	v_cvt_pk_bf16_f32 v6, v14, v15
	v_cvt_pk_bf16_f32 v7, v8, v9
	v_fmac_f32_e32 v18, v14, v14
	global_store_dwordx4 v[36:37], v[4:7], off offset:256
	v_fmac_f32_e32 v19, v8, v8
	s_nop 0
	v_add_f32_e32 v4, v16, v17
	v_add_f32_e32 v4, v4, v18
	v_add_f32_e32 v4, v19, v4
	v_add_f32_e32 v3, v3, v4
	v_mov_b32_e32 v4, v3
	s_nop 1
	v_permlane16_swap_b32_e32 v3, v4
	v_add_f32_e32 v3, v3, v4
	v_mov_b32_e32 v4, v3
	s_nop 1
	v_permlane32_swap_b32_e32 v3, v4
	v_add_f32_e32 v3, v3, v4
	v_mov_b32_e32 v233, v3
	s_and_saveexec_b64 s[28:29], s[2:3]
	global_atomic_add_f32 v[250:251], v226, off
	global_atomic_add_f32 v[250:251], v227, off offset:64
	global_atomic_add_f32 v[250:251], v228, off offset:128
	global_atomic_add_f32 v[250:251], v229, off offset:192
	global_atomic_add_f32 v[250:251], v230, off offset:512
	global_atomic_add_f32 v[250:251], v231, off offset:576
	global_atomic_add_f32 v[250:251], v232, off offset:640
	global_atomic_add_f32 v[250:251], v233, off offset:704
	s_or_b64 exec, exec, s[28:29]
	s_andn2_b64 vcc, exec, s[4:5]
	s_mov_b64 s[4:5], -1
	s_cbranch_vccnz .LBB0_405
	s_andn2_b64 vcc, exec, s[6:7]
	s_cbranch_vccnz .LBB0_404
	s_barrier
	s_branch .LBB0_404

; __device__ __forceinline__ unsigned cvt_pk_bf16(float lo, float hi) { unsigned r; asm volatile("v_cvt_pk_bf16_f32 %0, %1, %2" : "=v"(r) : "v"(lo), "v"(hi)); return r; }
;     __device__ __forceinline__ void operator()(const f32x4 (&acc)[2][2][4][2], const Unit& u, int wr, int wc, int fr, int fq) const {
;         const int row0 = row_base + u.pm * BM + wr * 64 + fr, col0 = u.pn * BM + wc * 32 + 8 * fq;
; #pragma unroll
;         for (int ai = 0; ai < 2; ++ai)
; #pragma unroll
;             for (int m = 0; m < 4; ++m) { const int row = row0 + ai * HALF + m * 16; bf16_t* rp = xb + (size_t)row * 2048 + col0; float s = 0.f;
; #pragma unroll
;                 for (int bj = 0; bj < 2; ++bj) { const u32x4 x = *(const u32x4*)(rp + bj * HALF); float v[8];
; #pragma unroll
;                     for (int e = 0; e < 4; ++e) { v[2 * e] = __builtin_bit_cast(float, x[e] << 16) + acc[ai][bj][m][e >> 1][(2 * e) & 3]; v[2 * e + 1] = __builtin_bit_cast(float, x[e] & 0xffff0000u) + acc[ai][bj][m][e >> 1][(2 * e + 1) & 3]; }
; #pragma unroll
;                     for (int e = 0; e < 8; ++e) s += v[e] * v[e];
;                     u32x4 w; w.x = cvt_pk_bf16(v[0], v[1]); w.y = cvt_pk_bf16(v[2], v[3]); w.z = cvt_pk_bf16(v[4], v[5]); w.w = cvt_pk_bf16(v[6], v[7]);
;                     *(u32x4*)(rp + bj * HALF) = w; }
;                 s = sum_x32(sum_x16(s)); asm volatile("" : "+v"(s));
;                 if (fq == 0) atomicAdd(ss + row, s); }
;     }
.LBB0_540:
	v_lshl_add_u32 v156, s61, 8, v170
	v_ashrrev_i32_e32 v157, 31, v156
	v_lshl_or_b32 v154, s60, 8, v172
	v_lshlrev_b64 v[176:177], 12, v[156:157]
	v_ashrrev_i32_e32 v155, 31, v154
	v_lshl_add_u64 v[176:177], s[16:17], 0, v[176:177]
	v_lshl_add_u64 v[180:181], v[154:155], 1, v[176:177]
	global_load_dwordx4 v[176:179], v[180:181], off
	s_waitcnt vmcnt(0)
	v_lshlrev_b32_e32 v182, 16, v176
	v_and_b32_e32 v176, 0xffff0000, v176
	v_lshlrev_b32_e32 v183, 16, v177
	v_and_b32_e32 v177, 0xffff0000, v177
	v_lshlrev_b32_e32 v184, 16, v178
	v_and_b32_e32 v178, 0xffff0000, v178
	v_lshlrev_b32_e32 v185, 16, v179
	v_and_b32_e32 v179, 0xffff0000, v179
	v_add_f32_e32 v182, v126, v182
	v_add_f32_e32 v176, v127, v176
	v_add_f32_e32 v183, v128, v183
	v_add_f32_e32 v177, v129, v177
	v_add_f32_e32 v184, v122, v184
	v_add_f32_e32 v178, v123, v178
	v_add_f32_e32 v185, v124, v185
	v_add_f32_e32 v179, v125, v179
	v_cvt_pk_bf16_f32 v122, v182, v176
	v_cvt_pk_bf16_f32 v123, v183, v177
	v_cvt_pk_bf16_f32 v124, v184, v178
	v_cvt_pk_bf16_f32 v125, v185, v179
	global_load_dwordx4 v[126:129], v[180:181], off offset:256
	v_mul_f32_e32 v176, v176, v176
	v_fmac_f32_e32 v176, v182, v182
	v_fmac_f32_e32 v176, v183, v183
	v_fmac_f32_e32 v176, v177, v177
	v_fmac_f32_e32 v176, v184, v184
	v_fmac_f32_e32 v176, v178, v178
	global_store_dwordx4 v[180:181], v[122:125], off
	v_fmac_f32_e32 v176, v185, v185
	v_fmac_f32_e32 v176, v179, v179
	s_waitcnt vmcnt(1)
	v_lshlrev_b32_e32 v122, 16, v126
	v_and_b32_e32 v123, 0xffff0000, v126
	v_add_f32_e32 v118, v118, v122
	v_lshlrev_b32_e32 v124, 16, v127
	v_add_f32_e32 v119, v119, v123
	v_fmac_f32_e32 v176, v118, v118
	v_and_b32_e32 v125, 0xffff0000, v127
	v_add_f32_e32 v120, v120, v124
	v_fmac_f32_e32 v176, v119, v119
	v_lshlrev_b32_e32 v126, 16, v128
	v_add_f32_e32 v121, v121, v125
	v_fmac_f32_e32 v176, v120, v120
	v_and_b32_e32 v127, 0xffff0000, v128
	v_add_f32_e32 v122, v114, v126
	v_fmac_f32_e32 v176, v121, v121
	v_lshlrev_b32_e32 v128, 16, v129
	v_add_f32_e32 v123, v115, v127
	v_fmac_f32_e32 v176, v122, v122
	v_and_b32_e32 v129, 0xffff0000, v129
	v_add_f32_e32 v124, v116, v128
	v_fmac_f32_e32 v176, v123, v123
	v_add_f32_e32 v125, v117, v129
	v_fmac_f32_e32 v176, v124, v124
	v_cvt_pk_bf16_f32 v114, v118, v119
	v_fmac_f32_e32 v176, v125, v125
	v_cvt_pk_bf16_f32 v115, v120, v121
	v_cvt_pk_bf16_f32 v116, v122, v123
	v_cvt_pk_bf16_f32 v117, v124, v125
	global_store_dwordx4 v[180:181], v[114:117], off offset:256
	s_nop 1
	v_mov_b32_e32 v114, v176
	s_nop 1
	v_permlane16_swap_b32_e32 v176, v114
	v_add_f32_e32 v114, v176, v114
	v_mov_b32_e32 v115, v114
	s_nop 1
	v_permlane32_swap_b32_e32 v114, v115
	v_add_f32_e32 v114, v114, v115
	v_mov_b32_e32 v200, v114
	v_lshl_add_u64 v[208:209], v[156:157], 2, s[22:23]
	v_or_b32_e32 v114, 16, v156
	v_ashrrev_i32_e32 v115, 31, v114
	v_lshlrev_b64 v[116:117], 12, v[114:115]
	v_lshl_add_u64 v[116:117], s[16:17], 0, v[116:117]
	v_lshl_add_u64 v[120:121], v[154:155], 1, v[116:117]
	global_load_dwordx4 v[116:119], v[120:121], off
	s_waitcnt vmcnt(0)
	v_lshlrev_b32_e32 v122, 16, v116
	v_and_b32_e32 v116, 0xffff0000, v116
	v_lshlrev_b32_e32 v123, 16, v117
	v_and_b32_e32 v117, 0xffff0000, v117
	v_lshlrev_b32_e32 v124, 16, v118
	v_and_b32_e32 v118, 0xffff0000, v118
	v_lshlrev_b32_e32 v125, 16, v119
	v_and_b32_e32 v119, 0xffff0000, v119
	v_add_f32_e32 v122, v110, v122
	v_add_f32_e32 v116, v111, v116
	v_add_f32_e32 v123, v112, v123
	v_add_f32_e32 v117, v113, v117
	v_add_f32_e32 v124, v106, v124
	v_add_f32_e32 v118, v107, v118
	v_add_f32_e32 v125, v108, v125
	v_add_f32_e32 v119, v109, v119
	v_cvt_pk_bf16_f32 v106, v122, v116
	v_cvt_pk_bf16_f32 v107, v123, v117
	v_cvt_pk_bf16_f32 v108, v124, v118
	v_cvt_pk_bf16_f32 v109, v125, v119
	global_load_dwordx4 v[110:113], v[120:121], off offset:256
	v_mul_f32_e32 v116, v116, v116
	v_fmac_f32_e32 v116, v122, v122
	v_fmac_f32_e32 v116, v123, v123
	v_fmac_f32_e32 v116, v117, v117
	v_fmac_f32_e32 v116, v124, v124
	v_fmac_f32_e32 v116, v118, v118
	global_store_dwordx4 v[120:121], v[106:109], off
	v_fmac_f32_e32 v116, v125, v125
	v_fmac_f32_e32 v116, v119, v119
	s_waitcnt vmcnt(1)
	v_lshlrev_b32_e32 v106, 16, v110
	v_and_b32_e32 v107, 0xffff0000, v110
	v_add_f32_e32 v102, v102, v106
	v_lshlrev_b32_e32 v108, 16, v111
	v_add_f32_e32 v103, v103, v107
	v_fmac_f32_e32 v116, v102, v102
	v_and_b32_e32 v109, 0xffff0000, v111
	v_add_f32_e32 v104, v104, v108
	v_fmac_f32_e32 v116, v103, v103
	v_lshlrev_b32_e32 v110, 16, v112
	v_add_f32_e32 v105, v105, v109
	v_fmac_f32_e32 v116, v104, v104
	v_and_b32_e32 v111, 0xffff0000, v112
	v_add_f32_e32 v106, v98, v110
	v_fmac_f32_e32 v116, v105, v105
	v_lshlrev_b32_e32 v112, 16, v113
	v_add_f32_e32 v107, v99, v111
	v_fmac_f32_e32 v116, v106, v106
	v_and_b32_e32 v113, 0xffff0000, v113
	v_add_f32_e32 v108, v100, v112
	v_fmac_f32_e32 v116, v107, v107
	v_add_f32_e32 v109, v101, v113
	v_fmac_f32_e32 v116, v108, v108
	v_cvt_pk_bf16_f32 v98, v102, v103
	v_fmac_f32_e32 v116, v109, v109
	v_cvt_pk_bf16_f32 v99, v104, v105
	v_cvt_pk_bf16_f32 v100, v106, v107
	v_cvt_pk_bf16_f32 v101, v108, v109
	global_store_dwordx4 v[120:121], v[98:101], off offset:256
	s_nop 1
	v_mov_b32_e32 v98, v116
	s_nop 1
	v_permlane16_swap_b32_e32 v116, v98
	v_add_f32_e32 v98, v116, v98
	v_mov_b32_e32 v99, v98
	s_nop 1
	v_permlane32_swap_b32_e32 v98, v99
	v_add_f32_e32 v98, v98, v99
	v_mov_b32_e32 v201, v98
	v_or_b32_e32 v98, 32, v156
	v_ashrrev_i32_e32 v99, 31, v98
	v_lshlrev_b64 v[100:101], 12, v[98:99]
	v_lshl_add_u64 v[100:101], s[16:17], 0, v[100:101]
	v_lshl_add_u64 v[104:105], v[154:155], 1, v[100:101]
	global_load_dwordx4 v[100:103], v[104:105], off
	s_waitcnt vmcnt(0)
; __device__ __forceinline__ unsigned cvt_pk_bf16(float lo, float hi) { unsigned r; asm volatile("v_cvt_pk_bf16_f32 %0, %1, %2" : "=v"(r) : "v"(lo), "v"(hi)); return r; }
;     __device__ __forceinline__ void operator()(const f32x4 (&acc)[2][2][4][2], const Unit& u, int wr, int wc, int fr, int fq) const {
;         const int row0 = row_base + u.pm * BM + wr * 64 + fr, col0 = u.pn * BM + wc * 32 + 8 * fq;
; #pragma unroll
;         for (int ai = 0; ai < 2; ++ai)
; #pragma unroll
;             for (int m = 0; m < 4; ++m) { const int row = row0 + ai * HALF + m * 16; bf16_t* rp = xb + (size_t)row * 2048 + col0; float s = 0.f;
; #pragma unroll
;                 for (int bj = 0; bj < 2; ++bj) { const u32x4 x = *(const u32x4*)(rp + bj * HALF); float v[8];
; #pragma unroll
;                     for (int e = 0; e < 4; ++e) { v[2 * e] = __builtin_bit_cast(float, x[e] << 16) + acc[ai][bj][m][e >> 1][(2 * e) & 3]; v[2 * e + 1] = __builtin_bit_cast(float, x[e] & 0xffff0000u) + acc[ai][bj][m][e >> 1][(2 * e + 1) & 3]; }
; #pragma unroll
;                     for (int e = 0; e < 8; ++e) s += v[e] * v[e];
;                     u32x4 w; w.x = cvt_pk_bf16(v[0], v[1]); w.y = cvt_pk_bf16(v[2], v[3]); w.z = cvt_pk_bf16(v[4], v[5]); w.w = cvt_pk_bf16(v[6], v[7]);
;                     *(u32x4*)(rp + bj * HALF) = w; }
;                 s = sum_x32(sum_x16(s)); asm volatile("" : "+v"(s));
;                 if (fq == 0) atomicAdd(ss + row, s); }
;     }
	v_lshlrev_b32_e32 v106, 16, v100
	v_and_b32_e32 v100, 0xffff0000, v100
	v_lshlrev_b32_e32 v107, 16, v101
	v_and_b32_e32 v101, 0xffff0000, v101
	v_lshlrev_b32_e32 v108, 16, v102
	v_and_b32_e32 v102, 0xffff0000, v102
	v_lshlrev_b32_e32 v109, 16, v103
	v_and_b32_e32 v103, 0xffff0000, v103
	v_add_f32_e32 v106, v94, v106
	v_add_f32_e32 v100, v95, v100
	v_add_f32_e32 v107, v96, v107
	v_add_f32_e32 v101, v97, v101
	v_add_f32_e32 v108, v90, v108
	v_add_f32_e32 v102, v91, v102
	v_add_f32_e32 v109, v92, v109
	v_add_f32_e32 v103, v93, v103
	v_cvt_pk_bf16_f32 v90, v106, v100
	v_cvt_pk_bf16_f32 v91, v107, v101
	v_cvt_pk_bf16_f32 v92, v108, v102
	v_cvt_pk_bf16_f32 v93, v109, v103
	global_load_dwordx4 v[94:97], v[104:105], off offset:256
	v_mul_f32_e32 v100, v100, v100
	v_fmac_f32_e32 v100, v106, v106
	v_fmac_f32_e32 v100, v107, v107
	v_fmac_f32_e32 v100, v101, v101
	v_fmac_f32_e32 v100, v108, v108
	v_fmac_f32_e32 v100, v102, v102
	global_store_dwordx4 v[104:105], v[90:93], off
	v_fmac_f32_e32 v100, v109, v109
	v_fmac_f32_e32 v100, v103, v103
	s_waitcnt vmcnt(1)
	v_lshlrev_b32_e32 v90, 16, v94
	v_and_b32_e32 v91, 0xffff0000, v94
	v_add_f32_e32 v86, v86, v90
	v_lshlrev_b32_e32 v92, 16, v95
	v_add_f32_e32 v87, v87, v91
	v_fmac_f32_e32 v100, v86, v86
	v_and_b32_e32 v93, 0xffff0000, v95
	v_add_f32_e32 v88, v88, v92
	v_fmac_f32_e32 v100, v87, v87
	v_lshlrev_b32_e32 v94, 16, v96
	v_add_f32_e32 v89, v89, v93
	v_fmac_f32_e32 v100, v88, v88
	v_and_b32_e32 v95, 0xffff0000, v96
	v_add_f32_e32 v90, v82, v94
	v_fmac_f32_e32 v100, v89, v89
	v_lshlrev_b32_e32 v96, 16, v97
	v_add_f32_e32 v91, v83, v95
	v_fmac_f32_e32 v100, v90, v90
	v_and_b32_e32 v97, 0xffff0000, v97
	v_add_f32_e32 v92, v84, v96
	v_fmac_f32_e32 v100, v91, v91
	v_add_f32_e32 v93, v85, v97
	v_fmac_f32_e32 v100, v92, v92
	v_cvt_pk_bf16_f32 v82, v86, v87
	v_fmac_f32_e32 v100, v93, v93
	v_cvt_pk_bf16_f32 v83, v88, v89
	v_cvt_pk_bf16_f32 v84, v90, v91
	v_cvt_pk_bf16_f32 v85, v92, v93
	global_store_dwordx4 v[104:105], v[82:85], off offset:256
	s_nop 1
	v_mov_b32_e32 v82, v100
	s_nop 1
	v_permlane16_swap_b32_e32 v100, v82
	v_add_f32_e32 v82, v100, v82
	v_mov_b32_e32 v83, v82
	s_nop 1
	v_permlane32_swap_b32_e32 v82, v83
	v_add_f32_e32 v82, v82, v83
	v_mov_b32_e32 v202, v82
	v_or_b32_e32 v82, 48, v156
	v_ashrrev_i32_e32 v83, 31, v82
	v_lshlrev_b64 v[84:85], 12, v[82:83]
	v_lshl_add_u64 v[84:85], s[16:17], 0, v[84:85]
	v_lshl_add_u64 v[88:89], v[154:155], 1, v[84:85]
	global_load_dwordx4 v[84:87], v[88:89], off
	s_waitcnt vmcnt(0)
	v_lshlrev_b32_e32 v90, 16, v84
	v_and_b32_e32 v84, 0xffff0000, v84
	v_lshlrev_b32_e32 v91, 16, v85
	v_and_b32_e32 v85, 0xffff0000, v85
	v_lshlrev_b32_e32 v92, 16, v86
	v_and_b32_e32 v86, 0xffff0000, v86
	v_lshlrev_b32_e32 v93, 16, v87
	v_and_b32_e32 v87, 0xffff0000, v87
	v_add_f32_e32 v90, v78, v90
	v_add_f32_e32 v84, v79, v84
	v_add_f32_e32 v91, v80, v91
	v_add_f32_e32 v85, v81, v85
	v_add_f32_e32 v92, v74, v92
	v_add_f32_e32 v86, v75, v86
	v_add_f32_e32 v93, v76, v93
	v_add_f32_e32 v87, v77, v87
	v_cvt_pk_bf16_f32 v74, v90, v84
	v_cvt_pk_bf16_f32 v75, v91, v85
	v_cvt_pk_bf16_f32 v76, v92, v86
	v_cvt_pk_bf16_f32 v77, v93, v87
	global_load_dwordx4 v[78:81], v[88:89], off offset:256
	v_mul_f32_e32 v84, v84, v84
	v_fmac_f32_e32 v84, v90, v90
	v_fmac_f32_e32 v84, v91, v91
	v_fmac_f32_e32 v84, v85, v85
	v_fmac_f32_e32 v84, v92, v92
	v_fmac_f32_e32 v84, v86, v86
	global_store_dwordx4 v[88:89], v[74:77], off
	v_fmac_f32_e32 v84, v93, v93
	v_fmac_f32_e32 v84, v87, v87
	s_waitcnt vmcnt(1)
	v_lshlrev_b32_e32 v74, 16, v78
	v_and_b32_e32 v75, 0xffff0000, v78
	v_add_f32_e32 v70, v70, v74
	v_lshlrev_b32_e32 v76, 16, v79
	v_add_f32_e32 v71, v71, v75
	v_fmac_f32_e32 v84, v70, v70
	v_and_b32_e32 v77, 0xffff0000, v79
	v_add_f32_e32 v72, v72, v76
	v_fmac_f32_e32 v84, v71, v71
	v_lshlrev_b32_e32 v78, 16, v80
	v_add_f32_e32 v73, v73, v77
	v_fmac_f32_e32 v84, v72, v72
	v_and_b32_e32 v79, 0xffff0000, v80
	v_add_f32_e32 v74, v66, v78
	v_fmac_f32_e32 v84, v73, v73
	v_lshlrev_b32_e32 v80, 16, v81
	v_add_f32_e32 v75, v67, v79
	v_fmac_f32_e32 v84, v74, v74
	v_and_b32_e32 v81, 0xffff0000, v81
	v_add_f32_e32 v76, v68, v80
	v_fmac_f32_e32 v84, v75, v75
	v_add_f32_e32 v77, v69, v81
	v_fmac_f32_e32 v84, v76, v76
	v_cvt_pk_bf16_f32 v66, v70, v71
	v_fmac_f32_e32 v84, v77, v77
	v_cvt_pk_bf16_f32 v67, v72, v73
	v_cvt_pk_bf16_f32 v68, v74, v75
	v_cvt_pk_bf16_f32 v69, v76, v77
	global_store_dwordx4 v[88:89], v[66:69], off offset:256
	s_nop 1
	v_mov_b32_e32 v66, v84
	s_nop 1
	v_permlane16_swap_b32_e32 v84, v66
	v_add_f32_e32 v66, v84, v66
	v_mov_b32_e32 v67, v66
	s_nop 1
	v_permlane32_swap_b32_e32 v66, v67
	v_add_f32_e32 v66, v66, v67
	v_mov_b32_e32 v203, v66
	v_add_u32_e32 v66, 0x80, v156
	v_ashrrev_i32_e32 v67, 31, v66
	v_lshlrev_b64 v[68:69], 12, v[66:67]
	v_lshl_add_u64 v[68:69], s[16:17], 0, v[68:69]
	v_lshl_add_u64 v[72:73], v[154:155], 1, v[68:69]
	global_load_dwordx4 v[68:71], v[72:73], off
	s_waitcnt vmcnt(0)
	v_lshlrev_b32_e32 v74, 16, v68
	v_and_b32_e32 v68, 0xffff0000, v68
	v_lshlrev_b32_e32 v75, 16, v69
	v_and_b32_e32 v69, 0xffff0000, v69
	v_lshlrev_b32_e32 v76, 16, v70
	v_and_b32_e32 v70, 0xffff0000, v70
	v_lshlrev_b32_e32 v77, 16, v71
	v_and_b32_e32 v71, 0xffff0000, v71
	v_add_f32_e32 v74, v62, v74
	v_add_f32_e32 v68, v63, v68
	v_add_f32_e32 v75, v64, v75
	v_add_f32_e32 v69, v65, v69
	v_add_f32_e32 v76, v58, v76
	v_add_f32_e32 v70, v59, v70
	v_add_f32_e32 v77, v60, v77
	v_add_f32_e32 v71, v61, v71
	v_cvt_pk_bf16_f32 v58, v74, v68
	v_cvt_pk_bf16_f32 v59, v75, v69
	v_cvt_pk_bf16_f32 v60, v76, v70
	v_cvt_pk_bf16_f32 v61, v77, v71
	global_load_dwordx4 v[62:65], v[72:73], off offset:256
	v_mul_f32_e32 v68, v68, v68
	v_fmac_f32_e32 v68, v74, v74
	v_fmac_f32_e32 v68, v75, v75
	v_fmac_f32_e32 v68, v69, v69
	v_fmac_f32_e32 v68, v76, v76
	v_fmac_f32_e32 v68, v70, v70
	global_store_dwordx4 v[72:73], v[58:61], off
	v_fmac_f32_e32 v68, v77, v77
	v_fmac_f32_e32 v68, v71, v71
	s_waitcnt vmcnt(1)
; __device__ __forceinline__ unsigned cvt_pk_bf16(float lo, float hi) { unsigned r; asm volatile("v_cvt_pk_bf16_f32 %0, %1, %2" : "=v"(r) : "v"(lo), "v"(hi)); return r; }
;     __device__ __forceinline__ void operator()(const f32x4 (&acc)[2][2][4][2], const Unit& u, int wr, int wc, int fr, int fq) const {
;         const int row0 = row_base + u.pm * BM + wr * 64 + fr, col0 = u.pn * BM + wc * 32 + 8 * fq;
; #pragma unroll
;         for (int ai = 0; ai < 2; ++ai)
; #pragma unroll
;             for (int m = 0; m < 4; ++m) { const int row = row0 + ai * HALF + m * 16; bf16_t* rp = xb + (size_t)row * 2048 + col0; float s = 0.f;
; #pragma unroll
;                 for (int bj = 0; bj < 2; ++bj) { const u32x4 x = *(const u32x4*)(rp + bj * HALF); float v[8];
; #pragma unroll
;                     for (int e = 0; e < 4; ++e) { v[2 * e] = __builtin_bit_cast(float, x[e] << 16) + acc[ai][bj][m][e >> 1][(2 * e) & 3]; v[2 * e + 1] = __builtin_bit_cast(float, x[e] & 0xffff0000u) + acc[ai][bj][m][e >> 1][(2 * e + 1) & 3]; }
; #pragma unroll
;                     for (int e = 0; e < 8; ++e) s += v[e] * v[e];
;                     u32x4 w; w.x = cvt_pk_bf16(v[0], v[1]); w.y = cvt_pk_bf16(v[2], v[3]); w.z = cvt_pk_bf16(v[4], v[5]); w.w = cvt_pk_bf16(v[6], v[7]);
;                     *(u32x4*)(rp + bj * HALF) = w; }
;                 s = sum_x32(sum_x16(s)); asm volatile("" : "+v"(s));
;                 if (fq == 0) atomicAdd(ss + row, s); }
;     }
	v_lshlrev_b32_e32 v58, 16, v62
	v_and_b32_e32 v59, 0xffff0000, v62
	v_add_f32_e32 v54, v54, v58
	v_lshlrev_b32_e32 v60, 16, v63
	v_add_f32_e32 v55, v55, v59
	v_fmac_f32_e32 v68, v54, v54
	v_and_b32_e32 v61, 0xffff0000, v63
	v_add_f32_e32 v56, v56, v60
	v_fmac_f32_e32 v68, v55, v55
	v_lshlrev_b32_e32 v62, 16, v64
	v_add_f32_e32 v57, v57, v61
	v_fmac_f32_e32 v68, v56, v56
	v_and_b32_e32 v63, 0xffff0000, v64
	v_add_f32_e32 v58, v50, v62
	v_fmac_f32_e32 v68, v57, v57
	v_lshlrev_b32_e32 v64, 16, v65
	v_add_f32_e32 v59, v51, v63
	v_fmac_f32_e32 v68, v58, v58
	v_and_b32_e32 v65, 0xffff0000, v65
	v_add_f32_e32 v60, v52, v64
	v_fmac_f32_e32 v68, v59, v59
	v_add_f32_e32 v61, v53, v65
	v_fmac_f32_e32 v68, v60, v60
	v_cvt_pk_bf16_f32 v50, v54, v55
	v_fmac_f32_e32 v68, v61, v61
	v_cvt_pk_bf16_f32 v51, v56, v57
	v_cvt_pk_bf16_f32 v52, v58, v59
	v_cvt_pk_bf16_f32 v53, v60, v61
	global_store_dwordx4 v[72:73], v[50:53], off offset:256
	s_nop 1
	v_mov_b32_e32 v50, v68
	s_nop 1
	v_permlane16_swap_b32_e32 v68, v50
	v_add_f32_e32 v50, v68, v50
	v_mov_b32_e32 v51, v50
	s_nop 1
	v_permlane32_swap_b32_e32 v50, v51
	v_add_f32_e32 v50, v50, v51
	v_mov_b32_e32 v204, v50
	v_add_u32_e32 v50, 0x90, v156
	v_ashrrev_i32_e32 v51, 31, v50
	v_lshlrev_b64 v[52:53], 12, v[50:51]
	v_lshl_add_u64 v[52:53], s[16:17], 0, v[52:53]
	v_lshl_add_u64 v[56:57], v[154:155], 1, v[52:53]
	global_load_dwordx4 v[52:55], v[56:57], off
	s_waitcnt vmcnt(0)
	v_lshlrev_b32_e32 v58, 16, v52
	v_and_b32_e32 v52, 0xffff0000, v52
	v_lshlrev_b32_e32 v59, 16, v53
	v_and_b32_e32 v53, 0xffff0000, v53
	v_lshlrev_b32_e32 v60, 16, v54
	v_and_b32_e32 v54, 0xffff0000, v54
	v_lshlrev_b32_e32 v61, 16, v55
	v_and_b32_e32 v55, 0xffff0000, v55
	v_add_f32_e32 v58, v46, v58
	v_add_f32_e32 v52, v47, v52
	v_add_f32_e32 v59, v48, v59
	v_add_f32_e32 v53, v49, v53
	v_add_f32_e32 v60, v42, v60
	v_add_f32_e32 v54, v43, v54
	v_add_f32_e32 v61, v44, v61
	v_add_f32_e32 v55, v45, v55
	v_cvt_pk_bf16_f32 v42, v58, v52
	v_cvt_pk_bf16_f32 v43, v59, v53
	v_cvt_pk_bf16_f32 v44, v60, v54
	v_cvt_pk_bf16_f32 v45, v61, v55
	global_load_dwordx4 v[46:49], v[56:57], off offset:256
	v_mul_f32_e32 v52, v52, v52
	v_fmac_f32_e32 v52, v58, v58
	v_fmac_f32_e32 v52, v59, v59
	v_fmac_f32_e32 v52, v53, v53
	v_fmac_f32_e32 v52, v60, v60
	v_fmac_f32_e32 v52, v54, v54
	global_store_dwordx4 v[56:57], v[42:45], off
	v_fmac_f32_e32 v52, v61, v61
	v_fmac_f32_e32 v52, v55, v55
	s_waitcnt vmcnt(1)
	v_lshlrev_b32_e32 v42, 16, v46
	v_and_b32_e32 v43, 0xffff0000, v46
	v_add_f32_e32 v38, v38, v42
	v_lshlrev_b32_e32 v44, 16, v47
	v_add_f32_e32 v39, v39, v43
	v_fmac_f32_e32 v52, v38, v38
	v_and_b32_e32 v45, 0xffff0000, v47
	v_add_f32_e32 v40, v40, v44
	v_fmac_f32_e32 v52, v39, v39
	v_lshlrev_b32_e32 v46, 16, v48
	v_add_f32_e32 v41, v41, v45
	v_fmac_f32_e32 v52, v40, v40
	v_and_b32_e32 v47, 0xffff0000, v48
	v_add_f32_e32 v42, v34, v46
	v_fmac_f32_e32 v52, v41, v41
	v_lshlrev_b32_e32 v48, 16, v49
	v_add_f32_e32 v43, v35, v47
	v_fmac_f32_e32 v52, v42, v42
	v_and_b32_e32 v49, 0xffff0000, v49
	v_add_f32_e32 v44, v36, v48
	v_fmac_f32_e32 v52, v43, v43
	v_add_f32_e32 v45, v37, v49
	v_fmac_f32_e32 v52, v44, v44
	v_cvt_pk_bf16_f32 v34, v38, v39
	v_fmac_f32_e32 v52, v45, v45
	v_cvt_pk_bf16_f32 v35, v40, v41
	v_cvt_pk_bf16_f32 v36, v42, v43
	v_cvt_pk_bf16_f32 v37, v44, v45
	global_store_dwordx4 v[56:57], v[34:37], off offset:256
	s_nop 1
	v_mov_b32_e32 v34, v52
	s_nop 1
	v_permlane16_swap_b32_e32 v52, v34
	v_add_f32_e32 v34, v52, v34
	v_mov_b32_e32 v35, v34
	s_nop 1
	v_permlane32_swap_b32_e32 v34, v35
	v_add_f32_e32 v34, v34, v35
	v_mov_b32_e32 v205, v34
	v_add_u32_e32 v34, 0xa0, v156
	v_ashrrev_i32_e32 v35, 31, v34
	v_lshlrev_b64 v[36:37], 12, v[34:35]
	v_lshl_add_u64 v[36:37], s[16:17], 0, v[36:37]
	v_lshl_add_u64 v[40:41], v[154:155], 1, v[36:37]
	global_load_dwordx4 v[36:39], v[40:41], off
	s_waitcnt vmcnt(0)
	v_lshlrev_b32_e32 v42, 16, v36
	v_and_b32_e32 v36, 0xffff0000, v36
	v_lshlrev_b32_e32 v43, 16, v37
	v_and_b32_e32 v37, 0xffff0000, v37
	v_lshlrev_b32_e32 v44, 16, v38
	v_and_b32_e32 v38, 0xffff0000, v38
	v_lshlrev_b32_e32 v45, 16, v39
	v_and_b32_e32 v39, 0xffff0000, v39
	v_add_f32_e32 v42, v30, v42
	v_add_f32_e32 v36, v31, v36
	v_add_f32_e32 v43, v32, v43
	v_add_f32_e32 v37, v33, v37
	v_add_f32_e32 v44, v26, v44
	v_add_f32_e32 v38, v27, v38
	v_add_f32_e32 v45, v28, v45
	v_add_f32_e32 v39, v29, v39
	v_cvt_pk_bf16_f32 v26, v42, v36
	v_cvt_pk_bf16_f32 v27, v43, v37
	v_cvt_pk_bf16_f32 v28, v44, v38
	v_cvt_pk_bf16_f32 v29, v45, v39
	global_load_dwordx4 v[30:33], v[40:41], off offset:256
	v_mul_f32_e32 v36, v36, v36
	v_fmac_f32_e32 v36, v42, v42
	v_fmac_f32_e32 v36, v43, v43
	v_fmac_f32_e32 v36, v37, v37
	v_fmac_f32_e32 v36, v44, v44
	v_fmac_f32_e32 v36, v38, v38
	global_store_dwordx4 v[40:41], v[26:29], off
	v_fmac_f32_e32 v36, v45, v45
	v_fmac_f32_e32 v36, v39, v39
	s_waitcnt vmcnt(1)
; __device__ __forceinline__ unsigned cvt_pk_bf16(float lo, float hi) { unsigned r; asm volatile("v_cvt_pk_bf16_f32 %0, %1, %2" : "=v"(r) : "v"(lo), "v"(hi)); return r; }
;     __device__ __forceinline__ void operator()(const f32x4 (&acc)[2][2][4][2], const Unit& u, int wr, int wc, int fr, int fq) const {
;         const int row0 = row_base + u.pm * BM + wr * 64 + fr, col0 = u.pn * BM + wc * 32 + 8 * fq;
; #pragma unroll
;         for (int ai = 0; ai < 2; ++ai)
; #pragma unroll
;             for (int m = 0; m < 4; ++m) { const int row = row0 + ai * HALF + m * 16; bf16_t* rp = xb + (size_t)row * 2048 + col0; float s = 0.f;
; #pragma unroll
;                 for (int bj = 0; bj < 2; ++bj) { const u32x4 x = *(const u32x4*)(rp + bj * HALF); float v[8];
; #pragma unroll
;                     for (int e = 0; e < 4; ++e) { v[2 * e] = __builtin_bit_cast(float, x[e] << 16) + acc[ai][bj][m][e >> 1][(2 * e) & 3]; v[2 * e + 1] = __builtin_bit_cast(float, x[e] & 0xffff0000u) + acc[ai][bj][m][e >> 1][(2 * e + 1) & 3]; }
; #pragma unroll
;                     for (int e = 0; e < 8; ++e) s += v[e] * v[e];
;                     u32x4 w; w.x = cvt_pk_bf16(v[0], v[1]); w.y = cvt_pk_bf16(v[2], v[3]); w.z = cvt_pk_bf16(v[4], v[5]); w.w = cvt_pk_bf16(v[6], v[7]);
;                     *(u32x4*)(rp + bj * HALF) = w; }
;                 s = sum_x32(sum_x16(s)); asm volatile("" : "+v"(s));
;                 if (fq == 0) atomicAdd(ss + row, s); }
;     }
	v_lshlrev_b32_e32 v26, 16, v30
	v_and_b32_e32 v27, 0xffff0000, v30
	v_add_f32_e32 v22, v22, v26
	v_lshlrev_b32_e32 v28, 16, v31
	v_add_f32_e32 v23, v23, v27
	v_fmac_f32_e32 v36, v22, v22
	v_and_b32_e32 v29, 0xffff0000, v31
	v_add_f32_e32 v24, v24, v28
	v_fmac_f32_e32 v36, v23, v23
	v_lshlrev_b32_e32 v30, 16, v32
	v_add_f32_e32 v25, v25, v29
	v_fmac_f32_e32 v36, v24, v24
	v_and_b32_e32 v31, 0xffff0000, v32
	v_add_f32_e32 v26, v18, v30
	v_fmac_f32_e32 v36, v25, v25
	v_lshlrev_b32_e32 v32, 16, v33
	v_add_f32_e32 v27, v19, v31
	v_fmac_f32_e32 v36, v26, v26
	v_and_b32_e32 v33, 0xffff0000, v33
	v_add_f32_e32 v28, v20, v32
	v_fmac_f32_e32 v36, v27, v27
	v_add_f32_e32 v29, v21, v33
	v_fmac_f32_e32 v36, v28, v28
	v_cvt_pk_bf16_f32 v18, v22, v23
	v_fmac_f32_e32 v36, v29, v29
	v_cvt_pk_bf16_f32 v19, v24, v25
	v_cvt_pk_bf16_f32 v20, v26, v27
	v_cvt_pk_bf16_f32 v21, v28, v29
	global_store_dwordx4 v[40:41], v[18:21], off offset:256
	s_nop 1
	v_mov_b32_e32 v18, v36
	s_nop 1
	v_permlane16_swap_b32_e32 v36, v18
	v_add_f32_e32 v18, v36, v18
	v_mov_b32_e32 v19, v18
	s_nop 1
	v_permlane32_swap_b32_e32 v18, v19
	v_add_f32_e32 v18, v18, v19
	v_mov_b32_e32 v206, v18
	v_add_u32_e32 v18, 0xb0, v156
	v_ashrrev_i32_e32 v19, 31, v18
	v_lshlrev_b64 v[20:21], 12, v[18:19]
	v_lshl_add_u64 v[20:21], s[16:17], 0, v[20:21]
	v_lshl_add_u64 v[24:25], v[154:155], 1, v[20:21]
	global_load_dwordx4 v[20:23], v[24:25], off
	s_waitcnt vmcnt(0)
	v_lshlrev_b32_e32 v26, 16, v20
	v_and_b32_e32 v20, 0xffff0000, v20
	v_lshlrev_b32_e32 v27, 16, v21
	v_and_b32_e32 v21, 0xffff0000, v21
	v_lshlrev_b32_e32 v28, 16, v22
	v_and_b32_e32 v22, 0xffff0000, v22
	v_lshlrev_b32_e32 v29, 16, v23
	v_and_b32_e32 v23, 0xffff0000, v23
	v_add_f32_e32 v26, v14, v26
	v_add_f32_e32 v20, v15, v20
	v_add_f32_e32 v27, v16, v27
	v_add_f32_e32 v21, v17, v21
	v_add_f32_e32 v28, v10, v28
	v_add_f32_e32 v22, v11, v22
	v_add_f32_e32 v29, v12, v29
	v_add_f32_e32 v23, v13, v23
	v_cvt_pk_bf16_f32 v10, v26, v20
	v_cvt_pk_bf16_f32 v11, v27, v21
	v_cvt_pk_bf16_f32 v12, v28, v22
	v_cvt_pk_bf16_f32 v13, v29, v23
	global_load_dwordx4 v[14:17], v[24:25], off offset:256
	v_mul_f32_e32 v20, v20, v20
	v_fmac_f32_e32 v20, v26, v26
	v_fmac_f32_e32 v20, v27, v27
	v_fmac_f32_e32 v20, v21, v21
	v_fmac_f32_e32 v20, v28, v28
	v_fmac_f32_e32 v20, v22, v22
	global_store_dwordx4 v[24:25], v[10:13], off
	v_fmac_f32_e32 v20, v29, v29
	v_fmac_f32_e32 v20, v23, v23
	s_waitcnt vmcnt(1)
	v_lshlrev_b32_e32 v10, 16, v14
	v_and_b32_e32 v11, 0xffff0000, v14
	v_add_f32_e32 v6, v6, v10
	v_lshlrev_b32_e32 v12, 16, v15
	v_add_f32_e32 v7, v7, v11
	v_fmac_f32_e32 v20, v6, v6
	v_and_b32_e32 v13, 0xffff0000, v15
	v_add_f32_e32 v8, v8, v12
	v_fmac_f32_e32 v20, v7, v7
	v_lshlrev_b32_e32 v14, 16, v16
	v_add_f32_e32 v9, v9, v13
	v_fmac_f32_e32 v20, v8, v8
	v_and_b32_e32 v15, 0xffff0000, v16
	v_add_f32_e32 v10, v2, v14
	v_fmac_f32_e32 v20, v9, v9
	v_lshlrev_b32_e32 v16, 16, v17
	v_add_f32_e32 v11, v3, v15
	v_fmac_f32_e32 v20, v10, v10
	v_and_b32_e32 v17, 0xffff0000, v17
	v_add_f32_e32 v12, v4, v16
	v_fmac_f32_e32 v20, v11, v11
	v_add_f32_e32 v13, v5, v17
	v_fmac_f32_e32 v20, v12, v12
	v_cvt_pk_bf16_f32 v2, v6, v7
	v_fmac_f32_e32 v20, v13, v13
	v_cvt_pk_bf16_f32 v3, v8, v9
	v_cvt_pk_bf16_f32 v4, v10, v11
	v_cvt_pk_bf16_f32 v5, v12, v13
	global_store_dwordx4 v[24:25], v[2:5], off offset:256
	s_nop 1
	v_mov_b32_e32 v2, v20
	s_nop 1
	v_permlane16_swap_b32_e32 v20, v2
	v_add_f32_e32 v2, v20, v2
	v_mov_b32_e32 v3, v2
	s_nop 1
	v_permlane32_swap_b32_e32 v2, v3
	v_add_f32_e32 v2, v2, v3
	v_mov_b32_e32 v207, v2
	s_and_saveexec_b64 s[36:37], s[4:5]
	global_atomic_add_f32 v[208:209], v200, off
	global_atomic_add_f32 v[208:209], v201, off offset:64
	global_atomic_add_f32 v[208:209], v202, off offset:128
	global_atomic_add_f32 v[208:209], v203, off offset:192
	global_atomic_add_f32 v[208:209], v204, off offset:512
	global_atomic_add_f32 v[208:209], v205, off offset:576
	global_atomic_add_f32 v[208:209], v206, off offset:640
	global_atomic_add_f32 v[208:209], v207, off offset:704
	s_or_b64 exec, exec, s[36:37]
	s_and_b64 vcc, exec, s[10:11]
	s_mov_b64 s[10:11], -1
	s_cbranch_vccnz .LBB0_525
	s_andn2_b64 vcc, exec, s[24:25]
	s_cbranch_vccnz .LBB0_524
	s_barrier
	s_branch .LBB0_524

; __device__ __forceinline__ unsigned cvt_pk_bf16(float lo, float hi) { unsigned r; asm volatile("v_cvt_pk_bf16_f32 %0, %1, %2" : "=v"(r) : "v"(lo), "v"(hi)); return r; }
;     __device__ __forceinline__ void operator()(const f32x4 (&acc)[2][2][4][2], const Unit& u, int wr, int wc, int fr, int fq) const {
;         const int row0 = row_base + u.pm * BM + wr * 64 + fr, col0 = u.pn * BM + wc * 32 + 8 * fq;
; #pragma unroll
;         for (int ai = 0; ai < 2; ++ai)
; #pragma unroll
;             for (int m = 0; m < 4; ++m) { const int row = row0 + ai * HALF + m * 16; bf16_t* rp = xb + (size_t)row * 2048 + col0; float s = 0.f;
; #pragma unroll
;                 for (int bj = 0; bj < 2; ++bj) { const u32x4 x = *(const u32x4*)(rp + bj * HALF); float v[8];
; #pragma unroll
;                     for (int e = 0; e < 4; ++e) { v[2 * e] = __builtin_bit_cast(float, x[e] << 16) + acc[ai][bj][m][e >> 1][(2 * e) & 3]; v[2 * e + 1] = __builtin_bit_cast(float, x[e] & 0xffff0000u) + acc[ai][bj][m][e >> 1][(2 * e + 1) & 3]; }
; #pragma unroll
;                     for (int e = 0; e < 8; ++e) s += v[e] * v[e];
;                     u32x4 w; w.x = cvt_pk_bf16(v[0], v[1]); w.y = cvt_pk_bf16(v[2], v[3]); w.z = cvt_pk_bf16(v[4], v[5]); w.w = cvt_pk_bf16(v[6], v[7]);
;                     *(u32x4*)(rp + bj * HALF) = w; }
;                 s = sum_x32(sum_x16(s)); asm volatile("" : "+v"(s));
;                 if (fq == 0) atomicAdd(ss + row, s); }
;     }
.LBB0_624:
	v_lshl_add_u32 v148, s52, 8, v151
	v_ashrrev_i32_e32 v149, 31, v148
	v_lshl_or_b32 v146, s51, 8, v152
	v_lshlrev_b64 v[156:157], 12, v[148:149]
	v_ashrrev_i32_e32 v147, 31, v146
	v_lshl_add_u64 v[156:157], s[16:17], 0, v[156:157]
	v_lshl_add_u64 v[160:161], v[146:147], 1, v[156:157]
	global_load_dwordx4 v[156:159], v[160:161], off
	s_waitcnt vmcnt(0)
	v_lshlrev_b32_e32 v155, 16, v156
	v_and_b32_e32 v156, 0xffff0000, v156
	v_lshlrev_b32_e32 v162, 16, v157
	v_and_b32_e32 v157, 0xffff0000, v157
	v_lshlrev_b32_e32 v163, 16, v158
	v_and_b32_e32 v158, 0xffff0000, v158
	v_lshlrev_b32_e32 v164, 16, v159
	v_and_b32_e32 v159, 0xffff0000, v159
	v_add_f32_e32 v155, v126, v155
	v_add_f32_e32 v156, v127, v156
	v_add_f32_e32 v162, v128, v162
	v_add_f32_e32 v157, v129, v157
	v_add_f32_e32 v163, v122, v163
	v_add_f32_e32 v158, v123, v158
	v_add_f32_e32 v164, v124, v164
	v_add_f32_e32 v159, v125, v159
	v_cvt_pk_bf16_f32 v122, v155, v156
	v_cvt_pk_bf16_f32 v123, v162, v157
	v_cvt_pk_bf16_f32 v124, v163, v158
	v_cvt_pk_bf16_f32 v125, v164, v159
	global_load_dwordx4 v[126:129], v[160:161], off offset:256
	v_mul_f32_e32 v156, v156, v156
	v_fmac_f32_e32 v156, v155, v155
	v_fmac_f32_e32 v156, v162, v162
	v_fmac_f32_e32 v156, v157, v157
	v_fmac_f32_e32 v156, v163, v163
	v_fmac_f32_e32 v156, v158, v158
	global_store_dwordx4 v[160:161], v[122:125], off
	v_fmac_f32_e32 v156, v164, v164
	v_fmac_f32_e32 v156, v159, v159
	s_waitcnt vmcnt(1)
	v_lshlrev_b32_e32 v122, 16, v126
	v_and_b32_e32 v123, 0xffff0000, v126
	v_add_f32_e32 v118, v118, v122
	v_lshlrev_b32_e32 v124, 16, v127
	v_add_f32_e32 v119, v119, v123
	v_fmac_f32_e32 v156, v118, v118
	v_and_b32_e32 v125, 0xffff0000, v127
	v_add_f32_e32 v120, v120, v124
	v_fmac_f32_e32 v156, v119, v119
	v_lshlrev_b32_e32 v126, 16, v128
	v_add_f32_e32 v121, v121, v125
	v_fmac_f32_e32 v156, v120, v120
	v_and_b32_e32 v127, 0xffff0000, v128
	v_add_f32_e32 v122, v114, v126
	v_fmac_f32_e32 v156, v121, v121
	v_lshlrev_b32_e32 v128, 16, v129
	v_add_f32_e32 v123, v115, v127
	v_fmac_f32_e32 v156, v122, v122
	v_and_b32_e32 v129, 0xffff0000, v129
	v_add_f32_e32 v124, v116, v128
	v_fmac_f32_e32 v156, v123, v123
	v_add_f32_e32 v125, v117, v129
	v_fmac_f32_e32 v156, v124, v124
	v_cvt_pk_bf16_f32 v114, v118, v119
	v_fmac_f32_e32 v156, v125, v125
	v_cvt_pk_bf16_f32 v115, v120, v121
	v_cvt_pk_bf16_f32 v116, v122, v123
	v_cvt_pk_bf16_f32 v117, v124, v125
	global_store_dwordx4 v[160:161], v[114:117], off offset:256
	s_nop 1
	v_mov_b32_e32 v114, v156
	s_nop 1
	v_permlane16_swap_b32_e32 v156, v114
	v_add_f32_e32 v114, v156, v114
	v_mov_b32_e32 v115, v114
	s_nop 1
	v_permlane32_swap_b32_e32 v114, v115
	v_add_f32_e32 v114, v114, v115
	v_mov_b32_e32 v200, v114
	v_lshl_add_u64 v[208:209], v[148:149], 2, s[22:23]
	v_or_b32_e32 v114, 16, v148
	v_ashrrev_i32_e32 v115, 31, v114
	v_lshlrev_b64 v[116:117], 12, v[114:115]
	v_lshl_add_u64 v[116:117], s[16:17], 0, v[116:117]
	v_lshl_add_u64 v[120:121], v[146:147], 1, v[116:117]
	global_load_dwordx4 v[116:119], v[120:121], off
	s_waitcnt vmcnt(0)
	v_lshlrev_b32_e32 v122, 16, v116
	v_and_b32_e32 v116, 0xffff0000, v116
	v_lshlrev_b32_e32 v123, 16, v117
	v_and_b32_e32 v117, 0xffff0000, v117
	v_lshlrev_b32_e32 v124, 16, v118
	v_and_b32_e32 v118, 0xffff0000, v118
	v_lshlrev_b32_e32 v125, 16, v119
	v_and_b32_e32 v119, 0xffff0000, v119
	v_add_f32_e32 v122, v110, v122
	v_add_f32_e32 v116, v111, v116
	v_add_f32_e32 v123, v112, v123
	v_add_f32_e32 v117, v113, v117
	v_add_f32_e32 v124, v106, v124
	v_add_f32_e32 v118, v107, v118
	v_add_f32_e32 v125, v108, v125
	v_add_f32_e32 v119, v109, v119
	v_cvt_pk_bf16_f32 v106, v122, v116
	v_cvt_pk_bf16_f32 v107, v123, v117
	v_cvt_pk_bf16_f32 v108, v124, v118
	v_cvt_pk_bf16_f32 v109, v125, v119
	global_load_dwordx4 v[110:113], v[120:121], off offset:256
	v_mul_f32_e32 v116, v116, v116
	v_fmac_f32_e32 v116, v122, v122
	v_fmac_f32_e32 v116, v123, v123
	v_fmac_f32_e32 v116, v117, v117
	v_fmac_f32_e32 v116, v124, v124
	v_fmac_f32_e32 v116, v118, v118
	global_store_dwordx4 v[120:121], v[106:109], off
	v_fmac_f32_e32 v116, v125, v125
	v_fmac_f32_e32 v116, v119, v119
	s_waitcnt vmcnt(1)
	v_lshlrev_b32_e32 v106, 16, v110
	v_and_b32_e32 v107, 0xffff0000, v110
	v_add_f32_e32 v102, v102, v106
	v_lshlrev_b32_e32 v108, 16, v111
	v_add_f32_e32 v103, v103, v107
	v_fmac_f32_e32 v116, v102, v102
	v_and_b32_e32 v109, 0xffff0000, v111
	v_add_f32_e32 v104, v104, v108
	v_fmac_f32_e32 v116, v103, v103
	v_lshlrev_b32_e32 v110, 16, v112
	v_add_f32_e32 v105, v105, v109
	v_fmac_f32_e32 v116, v104, v104
	v_and_b32_e32 v111, 0xffff0000, v112
	v_add_f32_e32 v106, v98, v110
	v_fmac_f32_e32 v116, v105, v105
	v_lshlrev_b32_e32 v112, 16, v113
	v_add_f32_e32 v107, v99, v111
	v_fmac_f32_e32 v116, v106, v106
	v_and_b32_e32 v113, 0xffff0000, v113
	v_add_f32_e32 v108, v100, v112
	v_fmac_f32_e32 v116, v107, v107
	v_add_f32_e32 v109, v101, v113
	v_fmac_f32_e32 v116, v108, v108
	v_cvt_pk_bf16_f32 v98, v102, v103
	v_fmac_f32_e32 v116, v109, v109
	v_cvt_pk_bf16_f32 v99, v104, v105
	v_cvt_pk_bf16_f32 v100, v106, v107
	v_cvt_pk_bf16_f32 v101, v108, v109
	global_store_dwordx4 v[120:121], v[98:101], off offset:256
	s_nop 1
	v_mov_b32_e32 v98, v116
	s_nop 1
	v_permlane16_swap_b32_e32 v116, v98
	v_add_f32_e32 v98, v116, v98
	v_mov_b32_e32 v99, v98
	s_nop 1
	v_permlane32_swap_b32_e32 v98, v99
	v_add_f32_e32 v98, v98, v99
	v_mov_b32_e32 v201, v98
	v_or_b32_e32 v98, 32, v148
	v_ashrrev_i32_e32 v99, 31, v98
	v_lshlrev_b64 v[100:101], 12, v[98:99]
	v_lshl_add_u64 v[100:101], s[16:17], 0, v[100:101]
	v_lshl_add_u64 v[104:105], v[146:147], 1, v[100:101]
	global_load_dwordx4 v[100:103], v[104:105], off
	s_waitcnt vmcnt(0)
; __device__ __forceinline__ unsigned cvt_pk_bf16(float lo, float hi) { unsigned r; asm volatile("v_cvt_pk_bf16_f32 %0, %1, %2" : "=v"(r) : "v"(lo), "v"(hi)); return r; }
;     __device__ __forceinline__ void operator()(const f32x4 (&acc)[2][2][4][2], const Unit& u, int wr, int wc, int fr, int fq) const {
;         const int row0 = row_base + u.pm * BM + wr * 64 + fr, col0 = u.pn * BM + wc * 32 + 8 * fq;
; #pragma unroll
;         for (int ai = 0; ai < 2; ++ai)
; #pragma unroll
;             for (int m = 0; m < 4; ++m) { const int row = row0 + ai * HALF + m * 16; bf16_t* rp = xb + (size_t)row * 2048 + col0; float s = 0.f;
; #pragma unroll
;                 for (int bj = 0; bj < 2; ++bj) { const u32x4 x = *(const u32x4*)(rp + bj * HALF); float v[8];
; #pragma unroll
;                     for (int e = 0; e < 4; ++e) { v[2 * e] = __builtin_bit_cast(float, x[e] << 16) + acc[ai][bj][m][e >> 1][(2 * e) & 3]; v[2 * e + 1] = __builtin_bit_cast(float, x[e] & 0xffff0000u) + acc[ai][bj][m][e >> 1][(2 * e + 1) & 3]; }
; #pragma unroll
;                     for (int e = 0; e < 8; ++e) s += v[e] * v[e];
;                     u32x4 w; w.x = cvt_pk_bf16(v[0], v[1]); w.y = cvt_pk_bf16(v[2], v[3]); w.z = cvt_pk_bf16(v[4], v[5]); w.w = cvt_pk_bf16(v[6], v[7]);
;                     *(u32x4*)(rp + bj * HALF) = w; }
;                 s = sum_x32(sum_x16(s)); asm volatile("" : "+v"(s));
;                 if (fq == 0) atomicAdd(ss + row, s); }
;     }
	v_lshlrev_b32_e32 v106, 16, v100
	v_and_b32_e32 v100, 0xffff0000, v100
	v_lshlrev_b32_e32 v107, 16, v101
	v_and_b32_e32 v101, 0xffff0000, v101
	v_lshlrev_b32_e32 v108, 16, v102
	v_and_b32_e32 v102, 0xffff0000, v102
	v_lshlrev_b32_e32 v109, 16, v103
	v_and_b32_e32 v103, 0xffff0000, v103
	v_add_f32_e32 v106, v94, v106
	v_add_f32_e32 v100, v95, v100
	v_add_f32_e32 v107, v96, v107
	v_add_f32_e32 v101, v97, v101
	v_add_f32_e32 v108, v90, v108
	v_add_f32_e32 v102, v91, v102
	v_add_f32_e32 v109, v92, v109
	v_add_f32_e32 v103, v93, v103
	v_cvt_pk_bf16_f32 v90, v106, v100
	v_cvt_pk_bf16_f32 v91, v107, v101
	v_cvt_pk_bf16_f32 v92, v108, v102
	v_cvt_pk_bf16_f32 v93, v109, v103
	global_load_dwordx4 v[94:97], v[104:105], off offset:256
	v_mul_f32_e32 v100, v100, v100
	v_fmac_f32_e32 v100, v106, v106
	v_fmac_f32_e32 v100, v107, v107
	v_fmac_f32_e32 v100, v101, v101
	v_fmac_f32_e32 v100, v108, v108
	v_fmac_f32_e32 v100, v102, v102
	global_store_dwordx4 v[104:105], v[90:93], off
	v_fmac_f32_e32 v100, v109, v109
	v_fmac_f32_e32 v100, v103, v103
	s_waitcnt vmcnt(1)
	v_lshlrev_b32_e32 v90, 16, v94
	v_and_b32_e32 v91, 0xffff0000, v94
	v_add_f32_e32 v86, v86, v90
	v_lshlrev_b32_e32 v92, 16, v95
	v_add_f32_e32 v87, v87, v91
	v_fmac_f32_e32 v100, v86, v86
	v_and_b32_e32 v93, 0xffff0000, v95
	v_add_f32_e32 v88, v88, v92
	v_fmac_f32_e32 v100, v87, v87
	v_lshlrev_b32_e32 v94, 16, v96
	v_add_f32_e32 v89, v89, v93
	v_fmac_f32_e32 v100, v88, v88
	v_and_b32_e32 v95, 0xffff0000, v96
	v_add_f32_e32 v90, v82, v94
	v_fmac_f32_e32 v100, v89, v89
	v_lshlrev_b32_e32 v96, 16, v97
	v_add_f32_e32 v91, v83, v95
	v_fmac_f32_e32 v100, v90, v90
	v_and_b32_e32 v97, 0xffff0000, v97
	v_add_f32_e32 v92, v84, v96
	v_fmac_f32_e32 v100, v91, v91
	v_add_f32_e32 v93, v85, v97
	v_fmac_f32_e32 v100, v92, v92
	v_cvt_pk_bf16_f32 v82, v86, v87
	v_fmac_f32_e32 v100, v93, v93
	v_cvt_pk_bf16_f32 v83, v88, v89
	v_cvt_pk_bf16_f32 v84, v90, v91
	v_cvt_pk_bf16_f32 v85, v92, v93
	global_store_dwordx4 v[104:105], v[82:85], off offset:256
	s_nop 1
	v_mov_b32_e32 v82, v100
	s_nop 1
	v_permlane16_swap_b32_e32 v100, v82
	v_add_f32_e32 v82, v100, v82
	v_mov_b32_e32 v83, v82
	s_nop 1
	v_permlane32_swap_b32_e32 v82, v83
	v_add_f32_e32 v82, v82, v83
	v_mov_b32_e32 v202, v82
	v_or_b32_e32 v82, 48, v148
	v_ashrrev_i32_e32 v83, 31, v82
	v_lshlrev_b64 v[84:85], 12, v[82:83]
	v_lshl_add_u64 v[84:85], s[16:17], 0, v[84:85]
	v_lshl_add_u64 v[88:89], v[146:147], 1, v[84:85]
	global_load_dwordx4 v[84:87], v[88:89], off
	s_waitcnt vmcnt(0)
	v_lshlrev_b32_e32 v90, 16, v84
	v_and_b32_e32 v84, 0xffff0000, v84
	v_lshlrev_b32_e32 v91, 16, v85
	v_and_b32_e32 v85, 0xffff0000, v85
	v_lshlrev_b32_e32 v92, 16, v86
	v_and_b32_e32 v86, 0xffff0000, v86
	v_lshlrev_b32_e32 v93, 16, v87
	v_and_b32_e32 v87, 0xffff0000, v87
	v_add_f32_e32 v90, v78, v90
	v_add_f32_e32 v84, v79, v84
	v_add_f32_e32 v91, v80, v91
	v_add_f32_e32 v85, v81, v85
	v_add_f32_e32 v92, v74, v92
	v_add_f32_e32 v86, v75, v86
	v_add_f32_e32 v93, v76, v93
	v_add_f32_e32 v87, v77, v87
	v_cvt_pk_bf16_f32 v74, v90, v84
	v_cvt_pk_bf16_f32 v75, v91, v85
	v_cvt_pk_bf16_f32 v76, v92, v86
	v_cvt_pk_bf16_f32 v77, v93, v87
	global_load_dwordx4 v[78:81], v[88:89], off offset:256
	v_mul_f32_e32 v84, v84, v84
	v_fmac_f32_e32 v84, v90, v90
	v_fmac_f32_e32 v84, v91, v91
	v_fmac_f32_e32 v84, v85, v85
	v_fmac_f32_e32 v84, v92, v92
	v_fmac_f32_e32 v84, v86, v86
	global_store_dwordx4 v[88:89], v[74:77], off
	v_fmac_f32_e32 v84, v93, v93
	v_fmac_f32_e32 v84, v87, v87
	s_waitcnt vmcnt(1)
	v_lshlrev_b32_e32 v74, 16, v78
	v_and_b32_e32 v75, 0xffff0000, v78
	v_add_f32_e32 v70, v70, v74
	v_lshlrev_b32_e32 v76, 16, v79
	v_add_f32_e32 v71, v71, v75
	v_fmac_f32_e32 v84, v70, v70
	v_and_b32_e32 v77, 0xffff0000, v79
	v_add_f32_e32 v72, v72, v76
	v_fmac_f32_e32 v84, v71, v71
	v_lshlrev_b32_e32 v78, 16, v80
	v_add_f32_e32 v73, v73, v77
	v_fmac_f32_e32 v84, v72, v72
	v_and_b32_e32 v79, 0xffff0000, v80
	v_add_f32_e32 v74, v66, v78
	v_fmac_f32_e32 v84, v73, v73
	v_lshlrev_b32_e32 v80, 16, v81
	v_add_f32_e32 v75, v67, v79
	v_fmac_f32_e32 v84, v74, v74
	v_and_b32_e32 v81, 0xffff0000, v81
	v_add_f32_e32 v76, v68, v80
	v_fmac_f32_e32 v84, v75, v75
	v_add_f32_e32 v77, v69, v81
	v_fmac_f32_e32 v84, v76, v76
	v_cvt_pk_bf16_f32 v66, v70, v71
	v_fmac_f32_e32 v84, v77, v77
	v_cvt_pk_bf16_f32 v67, v72, v73
	v_cvt_pk_bf16_f32 v68, v74, v75
	v_cvt_pk_bf16_f32 v69, v76, v77
	global_store_dwordx4 v[88:89], v[66:69], off offset:256
	s_nop 1
	v_mov_b32_e32 v66, v84
	s_nop 1
	v_permlane16_swap_b32_e32 v84, v66
	v_add_f32_e32 v66, v84, v66
	v_mov_b32_e32 v67, v66
	s_nop 1
	v_permlane32_swap_b32_e32 v66, v67
	v_add_f32_e32 v66, v66, v67
	v_mov_b32_e32 v203, v66
	v_add_u32_e32 v66, 0x80, v148
	v_ashrrev_i32_e32 v67, 31, v66
	v_lshlrev_b64 v[68:69], 12, v[66:67]
	v_lshl_add_u64 v[68:69], s[16:17], 0, v[68:69]
	v_lshl_add_u64 v[72:73], v[146:147], 1, v[68:69]
	global_load_dwordx4 v[68:71], v[72:73], off
	s_waitcnt vmcnt(0)
	v_lshlrev_b32_e32 v74, 16, v68
	v_and_b32_e32 v68, 0xffff0000, v68
	v_lshlrev_b32_e32 v75, 16, v69
	v_and_b32_e32 v69, 0xffff0000, v69
	v_lshlrev_b32_e32 v76, 16, v70
	v_and_b32_e32 v70, 0xffff0000, v70
	v_lshlrev_b32_e32 v77, 16, v71
	v_and_b32_e32 v71, 0xffff0000, v71
	v_add_f32_e32 v74, v62, v74
	v_add_f32_e32 v68, v63, v68
	v_add_f32_e32 v75, v64, v75
	v_add_f32_e32 v69, v65, v69
	v_add_f32_e32 v76, v58, v76
	v_add_f32_e32 v70, v59, v70
	v_add_f32_e32 v77, v60, v77
	v_add_f32_e32 v71, v61, v71
	v_cvt_pk_bf16_f32 v58, v74, v68
	v_cvt_pk_bf16_f32 v59, v75, v69
	v_cvt_pk_bf16_f32 v60, v76, v70
	v_cvt_pk_bf16_f32 v61, v77, v71
	global_load_dwordx4 v[62:65], v[72:73], off offset:256
	v_mul_f32_e32 v68, v68, v68
	v_fmac_f32_e32 v68, v74, v74
	v_fmac_f32_e32 v68, v75, v75
	v_fmac_f32_e32 v68, v69, v69
	v_fmac_f32_e32 v68, v76, v76
	v_fmac_f32_e32 v68, v70, v70
	global_store_dwordx4 v[72:73], v[58:61], off
	v_fmac_f32_e32 v68, v77, v77
	v_fmac_f32_e32 v68, v71, v71
	s_waitcnt vmcnt(1)
; __device__ __forceinline__ unsigned cvt_pk_bf16(float lo, float hi) { unsigned r; asm volatile("v_cvt_pk_bf16_f32 %0, %1, %2" : "=v"(r) : "v"(lo), "v"(hi)); return r; }
;     __device__ __forceinline__ void operator()(const f32x4 (&acc)[2][2][4][2], const Unit& u, int wr, int wc, int fr, int fq) const {
;         const int row0 = row_base + u.pm * BM + wr * 64 + fr, col0 = u.pn * BM + wc * 32 + 8 * fq;
; #pragma unroll
;         for (int ai = 0; ai < 2; ++ai)
; #pragma unroll
;             for (int m = 0; m < 4; ++m) { const int row = row0 + ai * HALF + m * 16; bf16_t* rp = xb + (size_t)row * 2048 + col0; float s = 0.f;
; #pragma unroll
;                 for (int bj = 0; bj < 2; ++bj) { const u32x4 x = *(const u32x4*)(rp + bj * HALF); float v[8];
; #pragma unroll
;                     for (int e = 0; e < 4; ++e) { v[2 * e] = __builtin_bit_cast(float, x[e] << 16) + acc[ai][bj][m][e >> 1][(2 * e) & 3]; v[2 * e + 1] = __builtin_bit_cast(float, x[e] & 0xffff0000u) + acc[ai][bj][m][e >> 1][(2 * e + 1) & 3]; }
; #pragma unroll
;                     for (int e = 0; e < 8; ++e) s += v[e] * v[e];
;                     u32x4 w; w.x = cvt_pk_bf16(v[0], v[1]); w.y = cvt_pk_bf16(v[2], v[3]); w.z = cvt_pk_bf16(v[4], v[5]); w.w = cvt_pk_bf16(v[6], v[7]);
;                     *(u32x4*)(rp + bj * HALF) = w; }
;                 s = sum_x32(sum_x16(s)); asm volatile("" : "+v"(s));
;                 if (fq == 0) atomicAdd(ss + row, s); }
;     }
	v_lshlrev_b32_e32 v58, 16, v62
	v_and_b32_e32 v59, 0xffff0000, v62
	v_add_f32_e32 v54, v54, v58
	v_lshlrev_b32_e32 v60, 16, v63
	v_add_f32_e32 v55, v55, v59
	v_fmac_f32_e32 v68, v54, v54
	v_and_b32_e32 v61, 0xffff0000, v63
	v_add_f32_e32 v56, v56, v60
	v_fmac_f32_e32 v68, v55, v55
	v_lshlrev_b32_e32 v62, 16, v64
	v_add_f32_e32 v57, v57, v61
	v_fmac_f32_e32 v68, v56, v56
	v_and_b32_e32 v63, 0xffff0000, v64
	v_add_f32_e32 v58, v50, v62
	v_fmac_f32_e32 v68, v57, v57
	v_lshlrev_b32_e32 v64, 16, v65
	v_add_f32_e32 v59, v51, v63
	v_fmac_f32_e32 v68, v58, v58
	v_and_b32_e32 v65, 0xffff0000, v65
	v_add_f32_e32 v60, v52, v64
	v_fmac_f32_e32 v68, v59, v59
	v_add_f32_e32 v61, v53, v65
	v_fmac_f32_e32 v68, v60, v60
	v_cvt_pk_bf16_f32 v50, v54, v55
	v_fmac_f32_e32 v68, v61, v61
	v_cvt_pk_bf16_f32 v51, v56, v57
	v_cvt_pk_bf16_f32 v52, v58, v59
	v_cvt_pk_bf16_f32 v53, v60, v61
	global_store_dwordx4 v[72:73], v[50:53], off offset:256
	s_nop 1
	v_mov_b32_e32 v50, v68
	s_nop 1
	v_permlane16_swap_b32_e32 v68, v50
	v_add_f32_e32 v50, v68, v50
	v_mov_b32_e32 v51, v50
	s_nop 1
	v_permlane32_swap_b32_e32 v50, v51
	v_add_f32_e32 v50, v50, v51
	v_mov_b32_e32 v204, v50
	v_add_u32_e32 v50, 0x90, v148
	v_ashrrev_i32_e32 v51, 31, v50
	v_lshlrev_b64 v[52:53], 12, v[50:51]
	v_lshl_add_u64 v[52:53], s[16:17], 0, v[52:53]
	v_lshl_add_u64 v[56:57], v[146:147], 1, v[52:53]
	global_load_dwordx4 v[52:55], v[56:57], off
	s_waitcnt vmcnt(0)
	v_lshlrev_b32_e32 v58, 16, v52
	v_and_b32_e32 v52, 0xffff0000, v52
	v_lshlrev_b32_e32 v59, 16, v53
	v_and_b32_e32 v53, 0xffff0000, v53
	v_lshlrev_b32_e32 v60, 16, v54
	v_and_b32_e32 v54, 0xffff0000, v54
	v_lshlrev_b32_e32 v61, 16, v55
	v_and_b32_e32 v55, 0xffff0000, v55
	v_add_f32_e32 v58, v46, v58
	v_add_f32_e32 v52, v47, v52
	v_add_f32_e32 v59, v48, v59
	v_add_f32_e32 v53, v49, v53
	v_add_f32_e32 v60, v42, v60
	v_add_f32_e32 v54, v43, v54
	v_add_f32_e32 v61, v44, v61
	v_add_f32_e32 v55, v45, v55
	v_cvt_pk_bf16_f32 v42, v58, v52
	v_cvt_pk_bf16_f32 v43, v59, v53
	v_cvt_pk_bf16_f32 v44, v60, v54
	v_cvt_pk_bf16_f32 v45, v61, v55
	global_load_dwordx4 v[46:49], v[56:57], off offset:256
	v_mul_f32_e32 v52, v52, v52
	v_fmac_f32_e32 v52, v58, v58
	v_fmac_f32_e32 v52, v59, v59
	v_fmac_f32_e32 v52, v53, v53
	v_fmac_f32_e32 v52, v60, v60
	v_fmac_f32_e32 v52, v54, v54
	global_store_dwordx4 v[56:57], v[42:45], off
	v_fmac_f32_e32 v52, v61, v61
	v_fmac_f32_e32 v52, v55, v55
	s_waitcnt vmcnt(1)
	v_lshlrev_b32_e32 v42, 16, v46
	v_and_b32_e32 v43, 0xffff0000, v46
	v_add_f32_e32 v38, v38, v42
	v_lshlrev_b32_e32 v44, 16, v47
	v_add_f32_e32 v39, v39, v43
	v_fmac_f32_e32 v52, v38, v38
	v_and_b32_e32 v45, 0xffff0000, v47
	v_add_f32_e32 v40, v40, v44
	v_fmac_f32_e32 v52, v39, v39
	v_lshlrev_b32_e32 v46, 16, v48
	v_add_f32_e32 v41, v41, v45
	v_fmac_f32_e32 v52, v40, v40
	v_and_b32_e32 v47, 0xffff0000, v48
	v_add_f32_e32 v42, v34, v46
	v_fmac_f32_e32 v52, v41, v41
	v_lshlrev_b32_e32 v48, 16, v49
	v_add_f32_e32 v43, v35, v47
	v_fmac_f32_e32 v52, v42, v42
	v_and_b32_e32 v49, 0xffff0000, v49
	v_add_f32_e32 v44, v36, v48
	v_fmac_f32_e32 v52, v43, v43
	v_add_f32_e32 v45, v37, v49
	v_fmac_f32_e32 v52, v44, v44
	v_cvt_pk_bf16_f32 v34, v38, v39
	v_fmac_f32_e32 v52, v45, v45
	v_cvt_pk_bf16_f32 v35, v40, v41
	v_cvt_pk_bf16_f32 v36, v42, v43
	v_cvt_pk_bf16_f32 v37, v44, v45
	global_store_dwordx4 v[56:57], v[34:37], off offset:256
	s_nop 1
	v_mov_b32_e32 v34, v52
	s_nop 1
	v_permlane16_swap_b32_e32 v52, v34
	v_add_f32_e32 v34, v52, v34
	v_mov_b32_e32 v35, v34
	s_nop 1
	v_permlane32_swap_b32_e32 v34, v35
	v_add_f32_e32 v34, v34, v35
	v_mov_b32_e32 v205, v34
	v_add_u32_e32 v34, 0xa0, v148
	v_ashrrev_i32_e32 v35, 31, v34
	v_lshlrev_b64 v[36:37], 12, v[34:35]
	v_lshl_add_u64 v[36:37], s[16:17], 0, v[36:37]
	v_lshl_add_u64 v[40:41], v[146:147], 1, v[36:37]
	global_load_dwordx4 v[36:39], v[40:41], off
	s_waitcnt vmcnt(0)
	v_lshlrev_b32_e32 v42, 16, v36
	v_and_b32_e32 v36, 0xffff0000, v36
	v_lshlrev_b32_e32 v43, 16, v37
	v_and_b32_e32 v37, 0xffff0000, v37
	v_lshlrev_b32_e32 v44, 16, v38
	v_and_b32_e32 v38, 0xffff0000, v38
	v_lshlrev_b32_e32 v45, 16, v39
	v_and_b32_e32 v39, 0xffff0000, v39
	v_add_f32_e32 v42, v30, v42
	v_add_f32_e32 v36, v31, v36
	v_add_f32_e32 v43, v32, v43
	v_add_f32_e32 v37, v33, v37
	v_add_f32_e32 v44, v26, v44
	v_add_f32_e32 v38, v27, v38
	v_add_f32_e32 v45, v28, v45
	v_add_f32_e32 v39, v29, v39
	v_cvt_pk_bf16_f32 v26, v42, v36
	v_cvt_pk_bf16_f32 v27, v43, v37
	v_cvt_pk_bf16_f32 v28, v44, v38
	v_cvt_pk_bf16_f32 v29, v45, v39
	global_load_dwordx4 v[30:33], v[40:41], off offset:256
	v_mul_f32_e32 v36, v36, v36
	v_fmac_f32_e32 v36, v42, v42
	v_fmac_f32_e32 v36, v43, v43
	v_fmac_f32_e32 v36, v37, v37
	v_fmac_f32_e32 v36, v44, v44
	v_fmac_f32_e32 v36, v38, v38
	global_store_dwordx4 v[40:41], v[26:29], off
	v_fmac_f32_e32 v36, v45, v45
	v_fmac_f32_e32 v36, v39, v39
	s_waitcnt vmcnt(1)
; __device__ __forceinline__ unsigned cvt_pk_bf16(float lo, float hi) { unsigned r; asm volatile("v_cvt_pk_bf16_f32 %0, %1, %2" : "=v"(r) : "v"(lo), "v"(hi)); return r; }
;     __device__ __forceinline__ void operator()(const f32x4 (&acc)[2][2][4][2], const Unit& u, int wr, int wc, int fr, int fq) const {
;         const int row0 = row_base + u.pm * BM + wr * 64 + fr, col0 = u.pn * BM + wc * 32 + 8 * fq;
; #pragma unroll
;         for (int ai = 0; ai < 2; ++ai)
; #pragma unroll
;             for (int m = 0; m < 4; ++m) { const int row = row0 + ai * HALF + m * 16; bf16_t* rp = xb + (size_t)row * 2048 + col0; float s = 0.f;
; #pragma unroll
;                 for (int bj = 0; bj < 2; ++bj) { const u32x4 x = *(const u32x4*)(rp + bj * HALF); float v[8];
; #pragma unroll
;                     for (int e = 0; e < 4; ++e) { v[2 * e] = __builtin_bit_cast(float, x[e] << 16) + acc[ai][bj][m][e >> 1][(2 * e) & 3]; v[2 * e + 1] = __builtin_bit_cast(float, x[e] & 0xffff0000u) + acc[ai][bj][m][e >> 1][(2 * e + 1) & 3]; }
; #pragma unroll
;                     for (int e = 0; e < 8; ++e) s += v[e] * v[e];
;                     u32x4 w; w.x = cvt_pk_bf16(v[0], v[1]); w.y = cvt_pk_bf16(v[2], v[3]); w.z = cvt_pk_bf16(v[4], v[5]); w.w = cvt_pk_bf16(v[6], v[7]);
;                     *(u32x4*)(rp + bj * HALF) = w; }
;                 s = sum_x32(sum_x16(s)); asm volatile("" : "+v"(s));
;                 if (fq == 0) atomicAdd(ss + row, s); }
;     }
	v_lshlrev_b32_e32 v26, 16, v30
	v_and_b32_e32 v27, 0xffff0000, v30
	v_add_f32_e32 v22, v22, v26
	v_lshlrev_b32_e32 v28, 16, v31
	v_add_f32_e32 v23, v23, v27
	v_fmac_f32_e32 v36, v22, v22
	v_and_b32_e32 v29, 0xffff0000, v31
	v_add_f32_e32 v24, v24, v28
	v_fmac_f32_e32 v36, v23, v23
	v_lshlrev_b32_e32 v30, 16, v32
	v_add_f32_e32 v25, v25, v29
	v_fmac_f32_e32 v36, v24, v24
	v_and_b32_e32 v31, 0xffff0000, v32
	v_add_f32_e32 v26, v18, v30
	v_fmac_f32_e32 v36, v25, v25
	v_lshlrev_b32_e32 v32, 16, v33
	v_add_f32_e32 v27, v19, v31
	v_fmac_f32_e32 v36, v26, v26
	v_and_b32_e32 v33, 0xffff0000, v33
	v_add_f32_e32 v28, v20, v32
	v_fmac_f32_e32 v36, v27, v27
	v_add_f32_e32 v29, v21, v33
	v_fmac_f32_e32 v36, v28, v28
	v_cvt_pk_bf16_f32 v18, v22, v23
	v_fmac_f32_e32 v36, v29, v29
	v_cvt_pk_bf16_f32 v19, v24, v25
	v_cvt_pk_bf16_f32 v20, v26, v27
	v_cvt_pk_bf16_f32 v21, v28, v29
	global_store_dwordx4 v[40:41], v[18:21], off offset:256
	s_nop 1
	v_mov_b32_e32 v18, v36
	s_nop 1
	v_permlane16_swap_b32_e32 v36, v18
	v_add_f32_e32 v18, v36, v18
	v_mov_b32_e32 v19, v18
	s_nop 1
	v_permlane32_swap_b32_e32 v18, v19
	v_add_f32_e32 v18, v18, v19
	v_mov_b32_e32 v206, v18
	v_add_u32_e32 v18, 0xb0, v148
	v_ashrrev_i32_e32 v19, 31, v18
	v_lshlrev_b64 v[20:21], 12, v[18:19]
	v_lshl_add_u64 v[20:21], s[16:17], 0, v[20:21]
	v_lshl_add_u64 v[24:25], v[146:147], 1, v[20:21]
	global_load_dwordx4 v[20:23], v[24:25], off
	s_waitcnt vmcnt(0)
	v_lshlrev_b32_e32 v26, 16, v20
	v_and_b32_e32 v20, 0xffff0000, v20
	v_lshlrev_b32_e32 v27, 16, v21
	v_and_b32_e32 v21, 0xffff0000, v21
	v_lshlrev_b32_e32 v28, 16, v22
	v_and_b32_e32 v22, 0xffff0000, v22
	v_lshlrev_b32_e32 v29, 16, v23
	v_and_b32_e32 v23, 0xffff0000, v23
	v_add_f32_e32 v26, v14, v26
	v_add_f32_e32 v20, v15, v20
	v_add_f32_e32 v27, v16, v27
	v_add_f32_e32 v21, v17, v21
	v_add_f32_e32 v28, v10, v28
	v_add_f32_e32 v22, v11, v22
	v_add_f32_e32 v29, v12, v29
	v_add_f32_e32 v23, v13, v23
	v_cvt_pk_bf16_f32 v10, v26, v20
	v_cvt_pk_bf16_f32 v11, v27, v21
	v_cvt_pk_bf16_f32 v12, v28, v22
	v_cvt_pk_bf16_f32 v13, v29, v23
	global_load_dwordx4 v[14:17], v[24:25], off offset:256
	v_mul_f32_e32 v20, v20, v20
	v_fmac_f32_e32 v20, v26, v26
	v_fmac_f32_e32 v20, v27, v27
	v_fmac_f32_e32 v20, v21, v21
	v_fmac_f32_e32 v20, v28, v28
	v_fmac_f32_e32 v20, v22, v22
	global_store_dwordx4 v[24:25], v[10:13], off
	v_fmac_f32_e32 v20, v29, v29
	v_fmac_f32_e32 v20, v23, v23
	s_waitcnt vmcnt(1)
	v_lshlrev_b32_e32 v10, 16, v14
	v_and_b32_e32 v11, 0xffff0000, v14
	v_add_f32_e32 v6, v6, v10
	v_lshlrev_b32_e32 v12, 16, v15
	v_add_f32_e32 v7, v7, v11
	v_fmac_f32_e32 v20, v6, v6
	v_and_b32_e32 v13, 0xffff0000, v15
	v_add_f32_e32 v8, v8, v12
	v_fmac_f32_e32 v20, v7, v7
	v_lshlrev_b32_e32 v14, 16, v16
	v_add_f32_e32 v9, v9, v13
	v_fmac_f32_e32 v20, v8, v8
	v_and_b32_e32 v15, 0xffff0000, v16
	v_add_f32_e32 v10, v2, v14
	v_fmac_f32_e32 v20, v9, v9
	v_lshlrev_b32_e32 v16, 16, v17
	v_add_f32_e32 v11, v3, v15
	v_fmac_f32_e32 v20, v10, v10
	v_and_b32_e32 v17, 0xffff0000, v17
	v_add_f32_e32 v12, v4, v16
	v_fmac_f32_e32 v20, v11, v11
	v_add_f32_e32 v13, v5, v17
	v_fmac_f32_e32 v20, v12, v12
	v_cvt_pk_bf16_f32 v2, v6, v7
	v_fmac_f32_e32 v20, v13, v13
	v_cvt_pk_bf16_f32 v3, v8, v9
	v_cvt_pk_bf16_f32 v4, v10, v11
	v_cvt_pk_bf16_f32 v5, v12, v13
	global_store_dwordx4 v[24:25], v[2:5], off offset:256
	s_nop 1
	v_mov_b32_e32 v2, v20
	s_nop 1
	v_permlane16_swap_b32_e32 v20, v2
	v_add_f32_e32 v2, v20, v2
	v_mov_b32_e32 v3, v2
	s_nop 1
	v_permlane32_swap_b32_e32 v2, v3
	v_add_f32_e32 v2, v2, v3
	v_mov_b32_e32 v207, v2
	s_and_saveexec_b64 s[24:25], s[4:5]
	global_atomic_add_f32 v[208:209], v200, off
	global_atomic_add_f32 v[208:209], v201, off offset:64
	global_atomic_add_f32 v[208:209], v202, off offset:128
	global_atomic_add_f32 v[208:209], v203, off offset:192
	global_atomic_add_f32 v[208:209], v204, off offset:512
	global_atomic_add_f32 v[208:209], v205, off offset:576
	global_atomic_add_f32 v[208:209], v206, off offset:640
	global_atomic_add_f32 v[208:209], v207, off offset:704
	s_or_b64 exec, exec, s[24:25]
	s_mov_b64 s[24:25], -1
	s_and_b64 vcc, exec, s[6:7]
	s_cbranch_vccz .LBB0_609
	s_andn2_b64 vcc, exec, s[10:11]
	s_cbranch_vccnz .LBB0_608
	s_barrier
	s_branch .LBB0_608
